# nt policy also on the once-read f32 residual input (layer-0 out-proj epilogue) and on the write-once f32 output stores
# speedup vs baseline: 1.0824x; 1.0090x over previous
; DEVI float lo2f(unsigned u) { return __uint_as_float(u << 16); }
; DEVI float hi2f(unsigned u) { return __uint_as_float(u & 0xffff0000u); }
; DEVI void phase_resid_gemm(const Params& p, const bfu* A, int lda, int nkt, const bfu* wT, int ldb, const float* resid32,
;                            float* ssq_out, float* out32, char* lds) {
;     ...
;       for (int ni = 0; ni < 4; ++ni) {
;         const int n = n0 + wn * 64 + ni * 16 + fq * 4;
;         float4 r;
;         if (resid32) r = *(const float4*)(resid32 + (long)m * 1024 + n);
;         else { const uint2 u = *(const uint2*)(xs + (long)m * LDX + n); r = make_float4(lo2f(u.x), hi2f(u.x), lo2f(u.y), hi2f(u.y)); }
;         float4 o;
;         o.x = r.x + acc[ni][mi][0]; o.y = r.y + acc[ni][mi][1]; o.z = r.z + acc[ni][mi][2]; o.w = r.w + acc[ni][mi][3];
;         if (out32) *(float4*)(out32 + (long)m * 1024 + n) = o;
.LBB0_38:
	s_lshl_b32 s20, s25, 8
	v_add_u32_e32 v132, s20, v179
	v_or_b32_e32 v130, s27, v181
	v_mov_b64_e32 v[126:127], s[2:3]
	v_mad_i64_i32 v[126:127], s[28:29], v132, s95, v[126:127]
	v_ashrrev_i32_e32 v131, 31, v130
	v_lshl_add_u64 v[134:135], v[130:131], 1, v[126:127]
	v_lshl_add_u64 v[218:219], v[134:135], 0, v[254:255]
	global_load_dwordx4 v[214:217], v[218:219], off
	v_ashrrev_i32_e32 v133, 31, v132
	v_lshlrev_b64 v[128:129], 12, v[132:133]
	v_cndmask_b32_e64 v0, 0, 1, s[46:47]
	v_lshl_add_u64 v[136:137], s[0:1], 0, v[128:129]
	s_mov_b64 s[36:37], -1
	v_cmp_ne_u32_e64 s[42:43], 1, v0
	s_andn2_b64 vcc, exec, s[46:47]
	v_lshl_add_u64 v[136:137], v[130:131], 2, v[136:137]
	s_waitcnt vmcnt(0)
	v_permlane16_swap_b32_e32 v214, v216
	v_permlane16_swap_b32_e32 v215, v217
	s_nop 1
	v_lshlrev_b32_e32 v128, 16, v214
	v_and_b32_e32 v129, 0xffff0000, v214
	v_lshlrev_b32_e32 v138, 16, v215
	v_and_b32_e32 v139, 0xffff0000, v215
	v_pk_add_f32 v[126:127], v[162:163], v[128:129]
	v_pk_add_f32 v[128:129], v[164:165], v[138:139]
	s_cbranch_vccnz .LBB0_40
	s_mov_b64 s[36:37], 0
	global_store_dwordx4 v[136:137], v[126:129], off nt

; DEVI float lo2f(unsigned u) { return __uint_as_float(u << 16); }
; DEVI float hi2f(unsigned u) { return __uint_as_float(u & 0xffff0000u); }
; DEVI void phase_resid_gemm(const Params& p, const bfu* A, int lda, int nkt, const bfu* wT, int ldb, const float* resid32,
;                            float* ssq_out, float* out32, char* lds) {
;     ...
;       for (int ni = 0; ni < 4; ++ni) {
;         const int n = n0 + wn * 64 + ni * 16 + fq * 4;
;         float4 r;
;         if (resid32) r = *(const float4*)(resid32 + (long)m * 1024 + n);
;         else { const uint2 u = *(const uint2*)(xs + (long)m * LDX + n); r = make_float4(lo2f(u.x), hi2f(u.x), lo2f(u.y), hi2f(u.y)); }
;         float4 o;
;         o.x = r.x + acc[ni][mi][0]; o.y = r.y + acc[ni][mi][1]; o.z = r.z + acc[ni][mi][2]; o.w = r.w + acc[ni][mi][3];
;         if (out32) *(float4*)(out32 + (long)m * 1024 + n) = o;
.LBB0_42:
	s_and_b64 vcc, exec, s[42:43]
	s_mov_b64 s[36:37], -1
	s_waitcnt vmcnt(0)
	v_lshlrev_b32_e32 v128, 16, v216
	v_and_b32_e32 v129, 0xffff0000, v216
	v_lshlrev_b32_e32 v126, 16, v217
	v_and_b32_e32 v127, 0xffff0000, v217
	v_pk_add_f32 v[122:123], v[122:123], v[128:129]
	v_pk_add_f32 v[124:125], v[124:125], v[126:127]
	s_cbranch_vccnz .LBB0_44
	s_mov_b64 s[36:37], 0
	global_store_dwordx4 v[136:137], v[122:125], off offset:64 nt

; DEVI float lo2f(unsigned u) { return __uint_as_float(u << 16); }
; DEVI float hi2f(unsigned u) { return __uint_as_float(u & 0xffff0000u); }
; DEVI void phase_resid_gemm(const Params& p, const bfu* A, int lda, int nkt, const bfu* wT, int ldb, const float* resid32,
;                            float* ssq_out, float* out32, char* lds) {
;     ...
;       for (int ni = 0; ni < 4; ++ni) {
;         const int n = n0 + wn * 64 + ni * 16 + fq * 4;
;         float4 r;
;         if (resid32) r = *(const float4*)(resid32 + (long)m * 1024 + n);
;         else { const uint2 u = *(const uint2*)(xs + (long)m * LDX + n); r = make_float4(lo2f(u.x), hi2f(u.x), lo2f(u.y), hi2f(u.y)); }
;         float4 o;
;         o.x = r.x + acc[ni][mi][0]; o.y = r.y + acc[ni][mi][1]; o.z = r.z + acc[ni][mi][2]; o.w = r.w + acc[ni][mi][3];
;         if (out32) *(float4*)(out32 + (long)m * 1024 + n) = o;
.LBB0_46:
	v_lshl_add_u64 v[218:219], v[134:135], 0, v[254:255]
	global_load_dwordx4 v[214:217], v[218:219], off offset:64
	s_and_b64 vcc, exec, s[42:43]
	s_mov_b64 s[36:37], -1
	s_waitcnt vmcnt(0)
	v_permlane16_swap_b32_e32 v214, v216
	v_permlane16_swap_b32_e32 v215, v217
	s_nop 1
	v_lshlrev_b32_e32 v124, 16, v214
	v_and_b32_e32 v125, 0xffff0000, v214
	v_lshlrev_b32_e32 v122, 16, v215
	v_and_b32_e32 v123, 0xffff0000, v215
	v_pk_add_f32 v[114:115], v[114:115], v[124:125]
	v_pk_add_f32 v[116:117], v[116:117], v[122:123]
	s_cbranch_vccnz .LBB0_48
	s_mov_b64 s[36:37], 0
	global_store_dwordx4 v[136:137], v[114:117], off offset:128 nt

; DEVI float lo2f(unsigned u) { return __uint_as_float(u << 16); }
; DEVI float hi2f(unsigned u) { return __uint_as_float(u & 0xffff0000u); }
; DEVI void phase_resid_gemm(const Params& p, const bfu* A, int lda, int nkt, const bfu* wT, int ldb, const float* resid32,
;                            float* ssq_out, float* out32, char* lds) {
;     ...
;       for (int ni = 0; ni < 4; ++ni) {
;         const int n = n0 + wn * 64 + ni * 16 + fq * 4;
;         float4 r;
;         if (resid32) r = *(const float4*)(resid32 + (long)m * 1024 + n);
;         else { const uint2 u = *(const uint2*)(xs + (long)m * LDX + n); r = make_float4(lo2f(u.x), hi2f(u.x), lo2f(u.y), hi2f(u.y)); }
;         float4 o;
;         o.x = r.x + acc[ni][mi][0]; o.y = r.y + acc[ni][mi][1]; o.z = r.z + acc[ni][mi][2]; o.w = r.w + acc[ni][mi][3];
;         if (out32) *(float4*)(out32 + (long)m * 1024 + n) = o;
.LBB0_53:
	global_store_dwordx4 v[136:137], v[110:113], off offset:192 nt
	s_cbranch_execnz .LBB0_52

; DEVI float lo2f(unsigned u) { return __uint_as_float(u << 16); }
; DEVI float hi2f(unsigned u) { return __uint_as_float(u & 0xffff0000u); }
; DEVI void phase_resid_gemm(const Params& p, const bfu* A, int lda, int nkt, const bfu* wT, int ldb, const float* resid32,
;                            float* ssq_out, float* out32, char* lds) {
;     ...
;       for (int ni = 0; ni < 4; ++ni) {
;         const int n = n0 + wn * 64 + ni * 16 + fq * 4;
;         float4 r;
;         if (resid32) r = *(const float4*)(resid32 + (long)m * 1024 + n);
;         else { const uint2 u = *(const uint2*)(xs + (long)m * LDX + n); r = make_float4(lo2f(u.x), hi2f(u.x), lo2f(u.y), hi2f(u.y)); }
;         float4 o;
;         o.x = r.x + acc[ni][mi][0]; o.y = r.y + acc[ni][mi][1]; o.z = r.z + acc[ni][mi][2]; o.w = r.w + acc[ni][mi][3];
;         if (out32) *(float4*)(out32 + (long)m * 1024 + n) = o;
.LBB0_58:
	s_waitcnt lgkmcnt(0)
	v_or_b32_e32 v110, 16, v132
	v_mov_b64_e32 v[112:113], s[2:3]
	v_mad_i64_i32 v[112:113], s[28:29], v110, s95, v[112:113]
	v_lshl_add_u64 v[114:115], v[130:131], 1, v[112:113]
	v_lshl_add_u64 v[218:219], v[114:115], 0, v[254:255]
	global_load_dwordx4 v[214:217], v[218:219], off
	v_ashrrev_i32_e32 v111, 31, v110
	v_lshlrev_b64 v[110:111], 12, v[110:111]
	v_lshl_add_u64 v[116:117], s[0:1], 0, v[110:111]
	s_mov_b64 s[36:37], -1
	s_and_b64 vcc, exec, s[42:43]
	v_lshl_add_u64 v[116:117], v[130:131], 2, v[116:117]
	s_waitcnt vmcnt(0)
	v_permlane16_swap_b32_e32 v214, v216
	v_permlane16_swap_b32_e32 v215, v217
	s_nop 1
	v_lshlrev_b32_e32 v110, 16, v214
	v_and_b32_e32 v111, 0xffff0000, v214
	v_lshlrev_b32_e32 v112, 16, v215
	v_and_b32_e32 v113, 0xffff0000, v215
	v_pk_add_f32 v[110:111], v[118:119], v[110:111]
	v_pk_add_f32 v[112:113], v[120:121], v[112:113]
	s_cbranch_vccnz .LBB0_60
	s_mov_b64 s[36:37], 0
	global_store_dwordx4 v[116:117], v[110:113], off nt

; DEVI float lo2f(unsigned u) { return __uint_as_float(u << 16); }
; DEVI float hi2f(unsigned u) { return __uint_as_float(u & 0xffff0000u); }
; DEVI void phase_resid_gemm(const Params& p, const bfu* A, int lda, int nkt, const bfu* wT, int ldb, const float* resid32,
;                            float* ssq_out, float* out32, char* lds) {
;     ...
;       for (int ni = 0; ni < 4; ++ni) {
;         const int n = n0 + wn * 64 + ni * 16 + fq * 4;
;         float4 r;
;         if (resid32) r = *(const float4*)(resid32 + (long)m * 1024 + n);
;         else { const uint2 u = *(const uint2*)(xs + (long)m * LDX + n); r = make_float4(lo2f(u.x), hi2f(u.x), lo2f(u.y), hi2f(u.y)); }
;         float4 o;
;         o.x = r.x + acc[ni][mi][0]; o.y = r.y + acc[ni][mi][1]; o.z = r.z + acc[ni][mi][2]; o.w = r.w + acc[ni][mi][3];
;         if (out32) *(float4*)(out32 + (long)m * 1024 + n) = o;
.LBB0_62:
	s_and_b64 vcc, exec, s[42:43]
	s_mov_b64 s[36:37], -1
	s_waitcnt vmcnt(0)
	v_lshlrev_b32_e32 v112, 16, v216
	v_and_b32_e32 v113, 0xffff0000, v216
	v_lshlrev_b32_e32 v110, 16, v217
	v_and_b32_e32 v111, 0xffff0000, v217
	v_pk_add_f32 v[106:107], v[106:107], v[112:113]
	v_pk_add_f32 v[108:109], v[108:109], v[110:111]
	s_cbranch_vccnz .LBB0_64
	s_mov_b64 s[36:37], 0
	global_store_dwordx4 v[116:117], v[106:109], off offset:64 nt

; DEVI float lo2f(unsigned u) { return __uint_as_float(u << 16); }
; DEVI float hi2f(unsigned u) { return __uint_as_float(u & 0xffff0000u); }
; DEVI void phase_resid_gemm(const Params& p, const bfu* A, int lda, int nkt, const bfu* wT, int ldb, const float* resid32,
;                            float* ssq_out, float* out32, char* lds) {
;     ...
;       for (int ni = 0; ni < 4; ++ni) {
;         const int n = n0 + wn * 64 + ni * 16 + fq * 4;
;         float4 r;
;         if (resid32) r = *(const float4*)(resid32 + (long)m * 1024 + n);
;         else { const uint2 u = *(const uint2*)(xs + (long)m * LDX + n); r = make_float4(lo2f(u.x), hi2f(u.x), lo2f(u.y), hi2f(u.y)); }
;         float4 o;
;         o.x = r.x + acc[ni][mi][0]; o.y = r.y + acc[ni][mi][1]; o.z = r.z + acc[ni][mi][2]; o.w = r.w + acc[ni][mi][3];
;         if (out32) *(float4*)(out32 + (long)m * 1024 + n) = o;
.LBB0_66:
	v_lshl_add_u64 v[218:219], v[114:115], 0, v[254:255]
	global_load_dwordx4 v[214:217], v[218:219], off offset:64
	s_and_b64 vcc, exec, s[42:43]
	s_mov_b64 s[36:37], -1
	s_waitcnt vmcnt(0)
	v_permlane16_swap_b32_e32 v214, v216
	v_permlane16_swap_b32_e32 v215, v217
	s_nop 1
	v_lshlrev_b32_e32 v108, 16, v214
	v_and_b32_e32 v109, 0xffff0000, v214
	v_lshlrev_b32_e32 v106, 16, v215
	v_and_b32_e32 v107, 0xffff0000, v215
	v_pk_add_f32 v[102:103], v[102:103], v[108:109]
	v_pk_add_f32 v[104:105], v[104:105], v[106:107]
	s_cbranch_vccnz .LBB0_68
	s_mov_b64 s[36:37], 0
	global_store_dwordx4 v[116:117], v[102:105], off offset:128 nt

; DEVI float lo2f(unsigned u) { return __uint_as_float(u << 16); }
; DEVI float hi2f(unsigned u) { return __uint_as_float(u & 0xffff0000u); }
; DEVI void phase_resid_gemm(const Params& p, const bfu* A, int lda, int nkt, const bfu* wT, int ldb, const float* resid32,
;                            float* ssq_out, float* out32, char* lds) {
;     ...
;       for (int ni = 0; ni < 4; ++ni) {
;         const int n = n0 + wn * 64 + ni * 16 + fq * 4;
;         float4 r;
;         if (resid32) r = *(const float4*)(resid32 + (long)m * 1024 + n);
;         else { const uint2 u = *(const uint2*)(xs + (long)m * LDX + n); r = make_float4(lo2f(u.x), hi2f(u.x), lo2f(u.y), hi2f(u.y)); }
;         float4 o;
;         o.x = r.x + acc[ni][mi][0]; o.y = r.y + acc[ni][mi][1]; o.z = r.z + acc[ni][mi][2]; o.w = r.w + acc[ni][mi][3];
;         if (out32) *(float4*)(out32 + (long)m * 1024 + n) = o;
.LBB0_73:
	global_store_dwordx4 v[116:117], v[94:97], off offset:192 nt
	s_cbranch_execnz .LBB0_72

; DEVI float lo2f(unsigned u) { return __uint_as_float(u << 16); }
; DEVI float hi2f(unsigned u) { return __uint_as_float(u & 0xffff0000u); }
; DEVI void phase_resid_gemm(const Params& p, const bfu* A, int lda, int nkt, const bfu* wT, int ldb, const float* resid32,
;                            float* ssq_out, float* out32, char* lds) {
;     ...
;       for (int ni = 0; ni < 4; ++ni) {
;         const int n = n0 + wn * 64 + ni * 16 + fq * 4;
;         float4 r;
;         if (resid32) r = *(const float4*)(resid32 + (long)m * 1024 + n);
;         else { const uint2 u = *(const uint2*)(xs + (long)m * LDX + n); r = make_float4(lo2f(u.x), hi2f(u.x), lo2f(u.y), hi2f(u.y)); }
;         float4 o;
;         o.x = r.x + acc[ni][mi][0]; o.y = r.y + acc[ni][mi][1]; o.z = r.z + acc[ni][mi][2]; o.w = r.w + acc[ni][mi][3];
;         if (out32) *(float4*)(out32 + (long)m * 1024 + n) = o;
.LBB0_78:
	s_waitcnt lgkmcnt(0)
	v_or_b32_e32 v94, 32, v132
	v_mov_b64_e32 v[96:97], s[2:3]
	v_mad_i64_i32 v[96:97], s[28:29], v94, s95, v[96:97]
	v_lshl_add_u64 v[102:103], v[130:131], 1, v[96:97]
	v_lshl_add_u64 v[218:219], v[102:103], 0, v[254:255]
	global_load_dwordx4 v[214:217], v[218:219], off
	v_ashrrev_i32_e32 v95, 31, v94
	v_lshlrev_b64 v[94:95], 12, v[94:95]
	v_lshl_add_u64 v[104:105], s[0:1], 0, v[94:95]
	s_mov_b64 s[36:37], -1
	s_and_b64 vcc, exec, s[42:43]
	s_waitcnt vmcnt(0)
	v_permlane16_swap_b32_e32 v214, v216
	v_permlane16_swap_b32_e32 v215, v217
	s_nop 1
	v_lshlrev_b32_e32 v94, 16, v214
	v_and_b32_e32 v95, 0xffff0000, v214
	v_lshlrev_b32_e32 v96, 16, v215
	v_and_b32_e32 v97, 0xffff0000, v215
	v_pk_add_f32 v[94:95], v[98:99], v[94:95]
	v_pk_add_f32 v[96:97], v[100:101], v[96:97]
	v_lshl_add_u64 v[98:99], v[130:131], 2, v[104:105]
	s_cbranch_vccnz .LBB0_80
	s_mov_b64 s[36:37], 0
	global_store_dwordx4 v[98:99], v[94:97], off nt

; DEVI float lo2f(unsigned u) { return __uint_as_float(u << 16); }
; DEVI float hi2f(unsigned u) { return __uint_as_float(u & 0xffff0000u); }
; DEVI void phase_resid_gemm(const Params& p, const bfu* A, int lda, int nkt, const bfu* wT, int ldb, const float* resid32,
;                            float* ssq_out, float* out32, char* lds) {
;     ...
;       for (int ni = 0; ni < 4; ++ni) {
;         const int n = n0 + wn * 64 + ni * 16 + fq * 4;
;         float4 r;
;         if (resid32) r = *(const float4*)(resid32 + (long)m * 1024 + n);
;         else { const uint2 u = *(const uint2*)(xs + (long)m * LDX + n); r = make_float4(lo2f(u.x), hi2f(u.x), lo2f(u.y), hi2f(u.y)); }
;         float4 o;
;         o.x = r.x + acc[ni][mi][0]; o.y = r.y + acc[ni][mi][1]; o.z = r.z + acc[ni][mi][2]; o.w = r.w + acc[ni][mi][3];
;         if (out32) *(float4*)(out32 + (long)m * 1024 + n) = o;
.LBB0_82:
	s_and_b64 vcc, exec, s[42:43]
	s_mov_b64 s[36:37], -1
	s_waitcnt vmcnt(0)
	v_lshlrev_b32_e32 v96, 16, v216
	v_and_b32_e32 v97, 0xffff0000, v216
	v_lshlrev_b32_e32 v94, 16, v217
	v_and_b32_e32 v95, 0xffff0000, v217
	v_pk_add_f32 v[90:91], v[90:91], v[96:97]
	v_pk_add_f32 v[92:93], v[92:93], v[94:95]
	s_cbranch_vccnz .LBB0_84
	s_mov_b64 s[36:37], 0
	global_store_dwordx4 v[98:99], v[90:93], off offset:64 nt

; DEVI float lo2f(unsigned u) { return __uint_as_float(u << 16); }
; DEVI float hi2f(unsigned u) { return __uint_as_float(u & 0xffff0000u); }
; DEVI void phase_resid_gemm(const Params& p, const bfu* A, int lda, int nkt, const bfu* wT, int ldb, const float* resid32,
;                            float* ssq_out, float* out32, char* lds) {
;     ...
;       for (int ni = 0; ni < 4; ++ni) {
;         const int n = n0 + wn * 64 + ni * 16 + fq * 4;
;         float4 r;
;         if (resid32) r = *(const float4*)(resid32 + (long)m * 1024 + n);
;         else { const uint2 u = *(const uint2*)(xs + (long)m * LDX + n); r = make_float4(lo2f(u.x), hi2f(u.x), lo2f(u.y), hi2f(u.y)); }
;         float4 o;
;         o.x = r.x + acc[ni][mi][0]; o.y = r.y + acc[ni][mi][1]; o.z = r.z + acc[ni][mi][2]; o.w = r.w + acc[ni][mi][3];
;         if (out32) *(float4*)(out32 + (long)m * 1024 + n) = o;
.LBB0_86:
	v_lshl_add_u64 v[218:219], v[102:103], 0, v[254:255]
	global_load_dwordx4 v[214:217], v[218:219], off offset:64
	s_and_b64 vcc, exec, s[42:43]
	s_mov_b64 s[36:37], -1
	s_waitcnt vmcnt(0)
	v_permlane16_swap_b32_e32 v214, v216
	v_permlane16_swap_b32_e32 v215, v217
	s_nop 1
	v_lshlrev_b32_e32 v92, 16, v214
	v_and_b32_e32 v93, 0xffff0000, v214
	v_lshlrev_b32_e32 v90, 16, v215
	v_and_b32_e32 v91, 0xffff0000, v215
	v_pk_add_f32 v[86:87], v[86:87], v[92:93]
	v_pk_add_f32 v[88:89], v[88:89], v[90:91]
	s_cbranch_vccnz .LBB0_88
	s_mov_b64 s[36:37], 0
	global_store_dwordx4 v[98:99], v[86:89], off offset:128 nt

; DEVI float lo2f(unsigned u) { return __uint_as_float(u << 16); }
; DEVI float hi2f(unsigned u) { return __uint_as_float(u & 0xffff0000u); }
; DEVI void phase_resid_gemm(const Params& p, const bfu* A, int lda, int nkt, const bfu* wT, int ldb, const float* resid32,
;                            float* ssq_out, float* out32, char* lds) {
;     ...
;       for (int ni = 0; ni < 4; ++ni) {
;         const int n = n0 + wn * 64 + ni * 16 + fq * 4;
;         float4 r;
;         if (resid32) r = *(const float4*)(resid32 + (long)m * 1024 + n);
;         else { const uint2 u = *(const uint2*)(xs + (long)m * LDX + n); r = make_float4(lo2f(u.x), hi2f(u.x), lo2f(u.y), hi2f(u.y)); }
;         float4 o;
;         o.x = r.x + acc[ni][mi][0]; o.y = r.y + acc[ni][mi][1]; o.z = r.z + acc[ni][mi][2]; o.w = r.w + acc[ni][mi][3];
;         if (out32) *(float4*)(out32 + (long)m * 1024 + n) = o;
.LBB0_93:
	global_store_dwordx4 v[98:99], v[78:81], off offset:192 nt
	s_cbranch_execnz .LBB0_92

; DEVI float lo2f(unsigned u) { return __uint_as_float(u << 16); }
; DEVI float hi2f(unsigned u) { return __uint_as_float(u & 0xffff0000u); }
; DEVI void phase_resid_gemm(const Params& p, const bfu* A, int lda, int nkt, const bfu* wT, int ldb, const float* resid32,
;                            float* ssq_out, float* out32, char* lds) {
;     ...
;       for (int ni = 0; ni < 4; ++ni) {
;         const int n = n0 + wn * 64 + ni * 16 + fq * 4;
;         float4 r;
;         if (resid32) r = *(const float4*)(resid32 + (long)m * 1024 + n);
;         else { const uint2 u = *(const uint2*)(xs + (long)m * LDX + n); r = make_float4(lo2f(u.x), hi2f(u.x), lo2f(u.y), hi2f(u.y)); }
;         float4 o;
;         o.x = r.x + acc[ni][mi][0]; o.y = r.y + acc[ni][mi][1]; o.z = r.z + acc[ni][mi][2]; o.w = r.w + acc[ni][mi][3];
;         if (out32) *(float4*)(out32 + (long)m * 1024 + n) = o;
.LBB0_98:
	s_waitcnt lgkmcnt(0)
	v_or_b32_e32 v78, 48, v132
	v_mov_b64_e32 v[80:81], s[2:3]
	v_mad_i64_i32 v[80:81], s[28:29], v78, s95, v[80:81]
	v_lshl_add_u64 v[86:87], v[130:131], 1, v[80:81]
	v_lshl_add_u64 v[218:219], v[86:87], 0, v[254:255]
	global_load_dwordx4 v[214:217], v[218:219], off
	v_ashrrev_i32_e32 v79, 31, v78
	v_lshlrev_b64 v[78:79], 12, v[78:79]
	v_lshl_add_u64 v[88:89], s[0:1], 0, v[78:79]
	s_mov_b64 s[36:37], -1
	s_and_b64 vcc, exec, s[42:43]
	s_waitcnt vmcnt(0)
	v_permlane16_swap_b32_e32 v214, v216
	v_permlane16_swap_b32_e32 v215, v217
	s_nop 1
	v_lshlrev_b32_e32 v78, 16, v214
	v_and_b32_e32 v79, 0xffff0000, v214
	v_lshlrev_b32_e32 v80, 16, v215
	v_and_b32_e32 v81, 0xffff0000, v215
	v_pk_add_f32 v[78:79], v[82:83], v[78:79]
	v_pk_add_f32 v[80:81], v[84:85], v[80:81]
	v_lshl_add_u64 v[82:83], v[130:131], 2, v[88:89]
	s_cbranch_vccnz .LBB0_100
	s_mov_b64 s[36:37], 0
	global_store_dwordx4 v[82:83], v[78:81], off nt

; DEVI float lo2f(unsigned u) { return __uint_as_float(u << 16); }
; DEVI float hi2f(unsigned u) { return __uint_as_float(u & 0xffff0000u); }
; DEVI void phase_resid_gemm(const Params& p, const bfu* A, int lda, int nkt, const bfu* wT, int ldb, const float* resid32,
;                            float* ssq_out, float* out32, char* lds) {
;     ...
;       for (int ni = 0; ni < 4; ++ni) {
;         const int n = n0 + wn * 64 + ni * 16 + fq * 4;
;         float4 r;
;         if (resid32) r = *(const float4*)(resid32 + (long)m * 1024 + n);
;         else { const uint2 u = *(const uint2*)(xs + (long)m * LDX + n); r = make_float4(lo2f(u.x), hi2f(u.x), lo2f(u.y), hi2f(u.y)); }
;         float4 o;
;         o.x = r.x + acc[ni][mi][0]; o.y = r.y + acc[ni][mi][1]; o.z = r.z + acc[ni][mi][2]; o.w = r.w + acc[ni][mi][3];
;         if (out32) *(float4*)(out32 + (long)m * 1024 + n) = o;
.LBB0_102:
	s_and_b64 vcc, exec, s[42:43]
	s_mov_b64 s[36:37], -1
	s_waitcnt vmcnt(0)
	v_lshlrev_b32_e32 v80, 16, v216
	v_and_b32_e32 v81, 0xffff0000, v216
	v_lshlrev_b32_e32 v78, 16, v217
	v_and_b32_e32 v79, 0xffff0000, v217
	v_pk_add_f32 v[74:75], v[74:75], v[80:81]
	v_pk_add_f32 v[76:77], v[76:77], v[78:79]
	s_cbranch_vccnz .LBB0_104
	s_mov_b64 s[36:37], 0
	global_store_dwordx4 v[82:83], v[74:77], off offset:64 nt

; DEVI float lo2f(unsigned u) { return __uint_as_float(u << 16); }
; DEVI float hi2f(unsigned u) { return __uint_as_float(u & 0xffff0000u); }
; DEVI void phase_resid_gemm(const Params& p, const bfu* A, int lda, int nkt, const bfu* wT, int ldb, const float* resid32,
;                            float* ssq_out, float* out32, char* lds) {
;     ...
;       for (int ni = 0; ni < 4; ++ni) {
;         const int n = n0 + wn * 64 + ni * 16 + fq * 4;
;         float4 r;
;         if (resid32) r = *(const float4*)(resid32 + (long)m * 1024 + n);
;         else { const uint2 u = *(const uint2*)(xs + (long)m * LDX + n); r = make_float4(lo2f(u.x), hi2f(u.x), lo2f(u.y), hi2f(u.y)); }
;         float4 o;
;         o.x = r.x + acc[ni][mi][0]; o.y = r.y + acc[ni][mi][1]; o.z = r.z + acc[ni][mi][2]; o.w = r.w + acc[ni][mi][3];
;         if (out32) *(float4*)(out32 + (long)m * 1024 + n) = o;
.LBB0_106:
	v_lshl_add_u64 v[218:219], v[86:87], 0, v[254:255]
	global_load_dwordx4 v[214:217], v[218:219], off offset:64
	s_and_b64 vcc, exec, s[42:43]
	s_mov_b64 s[36:37], -1
	s_waitcnt vmcnt(0)
	v_permlane16_swap_b32_e32 v214, v216
	v_permlane16_swap_b32_e32 v215, v217
	s_nop 1
	v_lshlrev_b32_e32 v76, 16, v214
	v_and_b32_e32 v77, 0xffff0000, v214
	v_lshlrev_b32_e32 v74, 16, v215
	v_and_b32_e32 v75, 0xffff0000, v215
	v_pk_add_f32 v[70:71], v[70:71], v[76:77]
	v_pk_add_f32 v[72:73], v[72:73], v[74:75]
	s_cbranch_vccnz .LBB0_108
	s_mov_b64 s[36:37], 0
	global_store_dwordx4 v[82:83], v[70:73], off offset:128 nt

; DEVI float lo2f(unsigned u) { return __uint_as_float(u << 16); }
; DEVI float hi2f(unsigned u) { return __uint_as_float(u & 0xffff0000u); }
; DEVI void phase_resid_gemm(const Params& p, const bfu* A, int lda, int nkt, const bfu* wT, int ldb, const float* resid32,
;                            float* ssq_out, float* out32, char* lds) {
;     ...
;       for (int ni = 0; ni < 4; ++ni) {
;         const int n = n0 + wn * 64 + ni * 16 + fq * 4;
;         float4 r;
;         if (resid32) r = *(const float4*)(resid32 + (long)m * 1024 + n);
;         else { const uint2 u = *(const uint2*)(xs + (long)m * LDX + n); r = make_float4(lo2f(u.x), hi2f(u.x), lo2f(u.y), hi2f(u.y)); }
;         float4 o;
;         o.x = r.x + acc[ni][mi][0]; o.y = r.y + acc[ni][mi][1]; o.z = r.z + acc[ni][mi][2]; o.w = r.w + acc[ni][mi][3];
;         if (out32) *(float4*)(out32 + (long)m * 1024 + n) = o;
.LBB0_113:
	global_store_dwordx4 v[82:83], v[62:65], off offset:192 nt
	s_cbranch_execnz .LBB0_112

; DEVI float lo2f(unsigned u) { return __uint_as_float(u << 16); }
; DEVI float hi2f(unsigned u) { return __uint_as_float(u & 0xffff0000u); }
; DEVI void phase_resid_gemm(const Params& p, const bfu* A, int lda, int nkt, const bfu* wT, int ldb, const float* resid32,
;                            float* ssq_out, float* out32, char* lds) {
;     ...
;       for (int ni = 0; ni < 4; ++ni) {
;         const int n = n0 + wn * 64 + ni * 16 + fq * 4;
;         float4 r;
;         if (resid32) r = *(const float4*)(resid32 + (long)m * 1024 + n);
;         else { const uint2 u = *(const uint2*)(xs + (long)m * LDX + n); r = make_float4(lo2f(u.x), hi2f(u.x), lo2f(u.y), hi2f(u.y)); }
;         float4 o;
;         o.x = r.x + acc[ni][mi][0]; o.y = r.y + acc[ni][mi][1]; o.z = r.z + acc[ni][mi][2]; o.w = r.w + acc[ni][mi][3];
;         if (out32) *(float4*)(out32 + (long)m * 1024 + n) = o;
.LBB0_118:
	s_waitcnt lgkmcnt(0)
	v_or_b32_e32 v62, 64, v132
	v_mov_b64_e32 v[64:65], s[2:3]
	v_mad_i64_i32 v[64:65], s[28:29], v62, s95, v[64:65]
	v_lshl_add_u64 v[70:71], v[130:131], 1, v[64:65]
	v_lshl_add_u64 v[218:219], v[70:71], 0, v[254:255]
	global_load_dwordx4 v[214:217], v[218:219], off
	v_ashrrev_i32_e32 v63, 31, v62
	v_lshlrev_b64 v[62:63], 12, v[62:63]
	v_lshl_add_u64 v[72:73], s[0:1], 0, v[62:63]
	s_mov_b64 s[36:37], -1
	s_and_b64 vcc, exec, s[42:43]
	s_waitcnt vmcnt(0)
	v_permlane16_swap_b32_e32 v214, v216
	v_permlane16_swap_b32_e32 v215, v217
	s_nop 1
	v_lshlrev_b32_e32 v62, 16, v214
	v_and_b32_e32 v63, 0xffff0000, v214
	v_lshlrev_b32_e32 v64, 16, v215
	v_and_b32_e32 v65, 0xffff0000, v215
	v_pk_add_f32 v[62:63], v[66:67], v[62:63]
	v_pk_add_f32 v[64:65], v[68:69], v[64:65]
	v_lshl_add_u64 v[66:67], v[130:131], 2, v[72:73]
	s_cbranch_vccnz .LBB0_120
	s_mov_b64 s[36:37], 0
	global_store_dwordx4 v[66:67], v[62:65], off nt

; DEVI float lo2f(unsigned u) { return __uint_as_float(u << 16); }
; DEVI float hi2f(unsigned u) { return __uint_as_float(u & 0xffff0000u); }
; DEVI void phase_resid_gemm(const Params& p, const bfu* A, int lda, int nkt, const bfu* wT, int ldb, const float* resid32,
;                            float* ssq_out, float* out32, char* lds) {
;     ...
;       for (int ni = 0; ni < 4; ++ni) {
;         const int n = n0 + wn * 64 + ni * 16 + fq * 4;
;         float4 r;
;         if (resid32) r = *(const float4*)(resid32 + (long)m * 1024 + n);
;         else { const uint2 u = *(const uint2*)(xs + (long)m * LDX + n); r = make_float4(lo2f(u.x), hi2f(u.x), lo2f(u.y), hi2f(u.y)); }
;         float4 o;
;         o.x = r.x + acc[ni][mi][0]; o.y = r.y + acc[ni][mi][1]; o.z = r.z + acc[ni][mi][2]; o.w = r.w + acc[ni][mi][3];
;         if (out32) *(float4*)(out32 + (long)m * 1024 + n) = o;
.LBB0_122:
	s_and_b64 vcc, exec, s[42:43]
	s_mov_b64 s[36:37], -1
	s_waitcnt vmcnt(0)
	v_lshlrev_b32_e32 v64, 16, v216
	v_and_b32_e32 v65, 0xffff0000, v216
	v_lshlrev_b32_e32 v62, 16, v217
	v_and_b32_e32 v63, 0xffff0000, v217
	v_pk_add_f32 v[58:59], v[58:59], v[64:65]
	v_pk_add_f32 v[60:61], v[60:61], v[62:63]
	s_cbranch_vccnz .LBB0_124
	s_mov_b64 s[36:37], 0
	global_store_dwordx4 v[66:67], v[58:61], off offset:64 nt

; DEVI float lo2f(unsigned u) { return __uint_as_float(u << 16); }
; DEVI float hi2f(unsigned u) { return __uint_as_float(u & 0xffff0000u); }
; DEVI void phase_resid_gemm(const Params& p, const bfu* A, int lda, int nkt, const bfu* wT, int ldb, const float* resid32,
;                            float* ssq_out, float* out32, char* lds) {
;     ...
;       for (int ni = 0; ni < 4; ++ni) {
;         const int n = n0 + wn * 64 + ni * 16 + fq * 4;
;         float4 r;
;         if (resid32) r = *(const float4*)(resid32 + (long)m * 1024 + n);
;         else { const uint2 u = *(const uint2*)(xs + (long)m * LDX + n); r = make_float4(lo2f(u.x), hi2f(u.x), lo2f(u.y), hi2f(u.y)); }
;         float4 o;
;         o.x = r.x + acc[ni][mi][0]; o.y = r.y + acc[ni][mi][1]; o.z = r.z + acc[ni][mi][2]; o.w = r.w + acc[ni][mi][3];
;         if (out32) *(float4*)(out32 + (long)m * 1024 + n) = o;
.LBB0_126:
	v_lshl_add_u64 v[218:219], v[70:71], 0, v[254:255]
	global_load_dwordx4 v[214:217], v[218:219], off offset:64
	s_and_b64 vcc, exec, s[42:43]
	s_mov_b64 s[36:37], -1
	s_waitcnt vmcnt(0)
	v_permlane16_swap_b32_e32 v214, v216
	v_permlane16_swap_b32_e32 v215, v217
	s_nop 1
	v_lshlrev_b32_e32 v60, 16, v214
	v_and_b32_e32 v61, 0xffff0000, v214
	v_lshlrev_b32_e32 v58, 16, v215
	v_and_b32_e32 v59, 0xffff0000, v215
	v_pk_add_f32 v[54:55], v[54:55], v[60:61]
	v_pk_add_f32 v[56:57], v[56:57], v[58:59]
	s_cbranch_vccnz .LBB0_128
	s_mov_b64 s[36:37], 0
	global_store_dwordx4 v[66:67], v[54:57], off offset:128 nt

; DEVI float lo2f(unsigned u) { return __uint_as_float(u << 16); }
; DEVI float hi2f(unsigned u) { return __uint_as_float(u & 0xffff0000u); }
; DEVI void phase_resid_gemm(const Params& p, const bfu* A, int lda, int nkt, const bfu* wT, int ldb, const float* resid32,
;                            float* ssq_out, float* out32, char* lds) {
;     ...
;       for (int ni = 0; ni < 4; ++ni) {
;         const int n = n0 + wn * 64 + ni * 16 + fq * 4;
;         float4 r;
;         if (resid32) r = *(const float4*)(resid32 + (long)m * 1024 + n);
;         else { const uint2 u = *(const uint2*)(xs + (long)m * LDX + n); r = make_float4(lo2f(u.x), hi2f(u.x), lo2f(u.y), hi2f(u.y)); }
;         float4 o;
;         o.x = r.x + acc[ni][mi][0]; o.y = r.y + acc[ni][mi][1]; o.z = r.z + acc[ni][mi][2]; o.w = r.w + acc[ni][mi][3];
;         if (out32) *(float4*)(out32 + (long)m * 1024 + n) = o;
.LBB0_133:
	global_store_dwordx4 v[66:67], v[46:49], off offset:192 nt
	s_cbranch_execnz .LBB0_132

; DEVI float lo2f(unsigned u) { return __uint_as_float(u << 16); }
; DEVI float hi2f(unsigned u) { return __uint_as_float(u & 0xffff0000u); }
; DEVI void phase_resid_gemm(const Params& p, const bfu* A, int lda, int nkt, const bfu* wT, int ldb, const float* resid32,
;                            float* ssq_out, float* out32, char* lds) {
;     ...
;       for (int ni = 0; ni < 4; ++ni) {
;         const int n = n0 + wn * 64 + ni * 16 + fq * 4;
;         float4 r;
;         if (resid32) r = *(const float4*)(resid32 + (long)m * 1024 + n);
;         else { const uint2 u = *(const uint2*)(xs + (long)m * LDX + n); r = make_float4(lo2f(u.x), hi2f(u.x), lo2f(u.y), hi2f(u.y)); }
;         float4 o;
;         o.x = r.x + acc[ni][mi][0]; o.y = r.y + acc[ni][mi][1]; o.z = r.z + acc[ni][mi][2]; o.w = r.w + acc[ni][mi][3];
;         if (out32) *(float4*)(out32 + (long)m * 1024 + n) = o;
.LBB0_138:
	s_waitcnt lgkmcnt(0)
	v_or_b32_e32 v46, 0x50, v132
	v_mov_b64_e32 v[48:49], s[2:3]
	v_mad_i64_i32 v[48:49], s[28:29], v46, s95, v[48:49]
	v_lshl_add_u64 v[54:55], v[130:131], 1, v[48:49]
	v_lshl_add_u64 v[218:219], v[54:55], 0, v[254:255]
	global_load_dwordx4 v[214:217], v[218:219], off
	v_ashrrev_i32_e32 v47, 31, v46
	v_lshlrev_b64 v[46:47], 12, v[46:47]
	v_lshl_add_u64 v[56:57], s[0:1], 0, v[46:47]
	s_mov_b64 s[36:37], -1
	s_and_b64 vcc, exec, s[42:43]
	s_waitcnt vmcnt(0)
	v_permlane16_swap_b32_e32 v214, v216
	v_permlane16_swap_b32_e32 v215, v217
	s_nop 1
	v_lshlrev_b32_e32 v46, 16, v214
	v_and_b32_e32 v47, 0xffff0000, v214
	v_lshlrev_b32_e32 v48, 16, v215
	v_and_b32_e32 v49, 0xffff0000, v215
	v_pk_add_f32 v[46:47], v[50:51], v[46:47]
	v_pk_add_f32 v[48:49], v[52:53], v[48:49]
	v_lshl_add_u64 v[50:51], v[130:131], 2, v[56:57]
	s_cbranch_vccnz .LBB0_140
	s_mov_b64 s[36:37], 0
	global_store_dwordx4 v[50:51], v[46:49], off nt

; DEVI float lo2f(unsigned u) { return __uint_as_float(u << 16); }
; DEVI float hi2f(unsigned u) { return __uint_as_float(u & 0xffff0000u); }
; DEVI void phase_resid_gemm(const Params& p, const bfu* A, int lda, int nkt, const bfu* wT, int ldb, const float* resid32,
;                            float* ssq_out, float* out32, char* lds) {
;     ...
;       for (int ni = 0; ni < 4; ++ni) {
;         const int n = n0 + wn * 64 + ni * 16 + fq * 4;
;         float4 r;
;         if (resid32) r = *(const float4*)(resid32 + (long)m * 1024 + n);
;         else { const uint2 u = *(const uint2*)(xs + (long)m * LDX + n); r = make_float4(lo2f(u.x), hi2f(u.x), lo2f(u.y), hi2f(u.y)); }
;         float4 o;
;         o.x = r.x + acc[ni][mi][0]; o.y = r.y + acc[ni][mi][1]; o.z = r.z + acc[ni][mi][2]; o.w = r.w + acc[ni][mi][3];
;         if (out32) *(float4*)(out32 + (long)m * 1024 + n) = o;
.LBB0_142:
	s_and_b64 vcc, exec, s[42:43]
	s_mov_b64 s[36:37], -1
	s_waitcnt vmcnt(0)
	v_lshlrev_b32_e32 v48, 16, v216
	v_and_b32_e32 v49, 0xffff0000, v216
	v_lshlrev_b32_e32 v46, 16, v217
	v_and_b32_e32 v47, 0xffff0000, v217
	v_pk_add_f32 v[42:43], v[42:43], v[48:49]
	v_pk_add_f32 v[44:45], v[44:45], v[46:47]
	s_cbranch_vccnz .LBB0_144
	s_mov_b64 s[36:37], 0
	global_store_dwordx4 v[50:51], v[42:45], off offset:64 nt

; DEVI float lo2f(unsigned u) { return __uint_as_float(u << 16); }
; DEVI float hi2f(unsigned u) { return __uint_as_float(u & 0xffff0000u); }
; DEVI void phase_resid_gemm(const Params& p, const bfu* A, int lda, int nkt, const bfu* wT, int ldb, const float* resid32,
;                            float* ssq_out, float* out32, char* lds) {
;     ...
;       for (int ni = 0; ni < 4; ++ni) {
;         const int n = n0 + wn * 64 + ni * 16 + fq * 4;
;         float4 r;
;         if (resid32) r = *(const float4*)(resid32 + (long)m * 1024 + n);
;         else { const uint2 u = *(const uint2*)(xs + (long)m * LDX + n); r = make_float4(lo2f(u.x), hi2f(u.x), lo2f(u.y), hi2f(u.y)); }
;         float4 o;
;         o.x = r.x + acc[ni][mi][0]; o.y = r.y + acc[ni][mi][1]; o.z = r.z + acc[ni][mi][2]; o.w = r.w + acc[ni][mi][3];
;         if (out32) *(float4*)(out32 + (long)m * 1024 + n) = o;
.LBB0_146:
	v_lshl_add_u64 v[218:219], v[54:55], 0, v[254:255]
	global_load_dwordx4 v[214:217], v[218:219], off offset:64
	s_and_b64 vcc, exec, s[42:43]
	s_mov_b64 s[36:37], -1
	s_waitcnt vmcnt(0)
	v_permlane16_swap_b32_e32 v214, v216
	v_permlane16_swap_b32_e32 v215, v217
	s_nop 1
	v_lshlrev_b32_e32 v44, 16, v214
	v_and_b32_e32 v45, 0xffff0000, v214
	v_lshlrev_b32_e32 v42, 16, v215
	v_and_b32_e32 v43, 0xffff0000, v215
	v_pk_add_f32 v[38:39], v[38:39], v[44:45]
	v_pk_add_f32 v[40:41], v[40:41], v[42:43]
	s_cbranch_vccnz .LBB0_148
	s_mov_b64 s[36:37], 0
	global_store_dwordx4 v[50:51], v[38:41], off offset:128 nt

; DEVI float lo2f(unsigned u) { return __uint_as_float(u << 16); }
; DEVI float hi2f(unsigned u) { return __uint_as_float(u & 0xffff0000u); }
; DEVI void phase_resid_gemm(const Params& p, const bfu* A, int lda, int nkt, const bfu* wT, int ldb, const float* resid32,
;                            float* ssq_out, float* out32, char* lds) {
;     ...
;       for (int ni = 0; ni < 4; ++ni) {
;         const int n = n0 + wn * 64 + ni * 16 + fq * 4;
;         float4 r;
;         if (resid32) r = *(const float4*)(resid32 + (long)m * 1024 + n);
;         else { const uint2 u = *(const uint2*)(xs + (long)m * LDX + n); r = make_float4(lo2f(u.x), hi2f(u.x), lo2f(u.y), hi2f(u.y)); }
;         float4 o;
;         o.x = r.x + acc[ni][mi][0]; o.y = r.y + acc[ni][mi][1]; o.z = r.z + acc[ni][mi][2]; o.w = r.w + acc[ni][mi][3];
;         if (out32) *(float4*)(out32 + (long)m * 1024 + n) = o;
.LBB0_153:
	global_store_dwordx4 v[50:51], v[30:33], off offset:192 nt
	s_cbranch_execnz .LBB0_152

; DEVI float lo2f(unsigned u) { return __uint_as_float(u << 16); }
; DEVI float hi2f(unsigned u) { return __uint_as_float(u & 0xffff0000u); }
; DEVI void phase_resid_gemm(const Params& p, const bfu* A, int lda, int nkt, const bfu* wT, int ldb, const float* resid32,
;                            float* ssq_out, float* out32, char* lds) {
;     ...
;       for (int ni = 0; ni < 4; ++ni) {
;         const int n = n0 + wn * 64 + ni * 16 + fq * 4;
;         float4 r;
;         if (resid32) r = *(const float4*)(resid32 + (long)m * 1024 + n);
;         else { const uint2 u = *(const uint2*)(xs + (long)m * LDX + n); r = make_float4(lo2f(u.x), hi2f(u.x), lo2f(u.y), hi2f(u.y)); }
;         float4 o;
;         o.x = r.x + acc[ni][mi][0]; o.y = r.y + acc[ni][mi][1]; o.z = r.z + acc[ni][mi][2]; o.w = r.w + acc[ni][mi][3];
;         if (out32) *(float4*)(out32 + (long)m * 1024 + n) = o;
.LBB0_158:
	s_waitcnt lgkmcnt(0)
	v_or_b32_e32 v30, 0x60, v132
	v_mov_b64_e32 v[32:33], s[2:3]
	v_mad_i64_i32 v[32:33], s[28:29], v30, s95, v[32:33]
	v_lshl_add_u64 v[38:39], v[130:131], 1, v[32:33]
	v_lshl_add_u64 v[218:219], v[38:39], 0, v[254:255]
	global_load_dwordx4 v[214:217], v[218:219], off
	v_ashrrev_i32_e32 v31, 31, v30
	v_lshlrev_b64 v[30:31], 12, v[30:31]
	v_lshl_add_u64 v[40:41], s[0:1], 0, v[30:31]
	s_mov_b64 s[36:37], -1
	s_and_b64 vcc, exec, s[42:43]
	s_waitcnt vmcnt(0)
	v_permlane16_swap_b32_e32 v214, v216
	v_permlane16_swap_b32_e32 v215, v217
	s_nop 1
	v_lshlrev_b32_e32 v30, 16, v214
	v_and_b32_e32 v31, 0xffff0000, v214
	v_lshlrev_b32_e32 v32, 16, v215
	v_and_b32_e32 v33, 0xffff0000, v215
	v_pk_add_f32 v[30:31], v[34:35], v[30:31]
	v_pk_add_f32 v[32:33], v[36:37], v[32:33]
	v_lshl_add_u64 v[34:35], v[130:131], 2, v[40:41]
	s_cbranch_vccnz .LBB0_160
	s_mov_b64 s[36:37], 0
	global_store_dwordx4 v[34:35], v[30:33], off nt

; DEVI float lo2f(unsigned u) { return __uint_as_float(u << 16); }
; DEVI float hi2f(unsigned u) { return __uint_as_float(u & 0xffff0000u); }
; DEVI void phase_resid_gemm(const Params& p, const bfu* A, int lda, int nkt, const bfu* wT, int ldb, const float* resid32,
;                            float* ssq_out, float* out32, char* lds) {
;     ...
;       for (int ni = 0; ni < 4; ++ni) {
;         const int n = n0 + wn * 64 + ni * 16 + fq * 4;
;         float4 r;
;         if (resid32) r = *(const float4*)(resid32 + (long)m * 1024 + n);
;         else { const uint2 u = *(const uint2*)(xs + (long)m * LDX + n); r = make_float4(lo2f(u.x), hi2f(u.x), lo2f(u.y), hi2f(u.y)); }
;         float4 o;
;         o.x = r.x + acc[ni][mi][0]; o.y = r.y + acc[ni][mi][1]; o.z = r.z + acc[ni][mi][2]; o.w = r.w + acc[ni][mi][3];
;         if (out32) *(float4*)(out32 + (long)m * 1024 + n) = o;
.LBB0_162:
	s_and_b64 vcc, exec, s[42:43]
	s_mov_b64 s[36:37], -1
	s_waitcnt vmcnt(0)
	v_lshlrev_b32_e32 v32, 16, v216
	v_and_b32_e32 v33, 0xffff0000, v216
	v_lshlrev_b32_e32 v30, 16, v217
	v_and_b32_e32 v31, 0xffff0000, v217
	v_pk_add_f32 v[26:27], v[26:27], v[32:33]
	v_pk_add_f32 v[28:29], v[28:29], v[30:31]
	s_cbranch_vccnz .LBB0_164
	s_mov_b64 s[36:37], 0
	global_store_dwordx4 v[34:35], v[26:29], off offset:64 nt

; DEVI float lo2f(unsigned u) { return __uint_as_float(u << 16); }
; DEVI float hi2f(unsigned u) { return __uint_as_float(u & 0xffff0000u); }
; DEVI void phase_resid_gemm(const Params& p, const bfu* A, int lda, int nkt, const bfu* wT, int ldb, const float* resid32,
;                            float* ssq_out, float* out32, char* lds) {
;     ...
;       for (int ni = 0; ni < 4; ++ni) {
;         const int n = n0 + wn * 64 + ni * 16 + fq * 4;
;         float4 r;
;         if (resid32) r = *(const float4*)(resid32 + (long)m * 1024 + n);
;         else { const uint2 u = *(const uint2*)(xs + (long)m * LDX + n); r = make_float4(lo2f(u.x), hi2f(u.x), lo2f(u.y), hi2f(u.y)); }
;         float4 o;
;         o.x = r.x + acc[ni][mi][0]; o.y = r.y + acc[ni][mi][1]; o.z = r.z + acc[ni][mi][2]; o.w = r.w + acc[ni][mi][3];
;         if (out32) *(float4*)(out32 + (long)m * 1024 + n) = o;
.LBB0_166:
	v_lshl_add_u64 v[218:219], v[38:39], 0, v[254:255]
	global_load_dwordx4 v[214:217], v[218:219], off offset:64
	s_and_b64 vcc, exec, s[42:43]
	s_mov_b64 s[36:37], -1
	s_waitcnt vmcnt(0)
	v_permlane16_swap_b32_e32 v214, v216
	v_permlane16_swap_b32_e32 v215, v217
	s_nop 1
	v_lshlrev_b32_e32 v28, 16, v214
	v_and_b32_e32 v29, 0xffff0000, v214
	v_lshlrev_b32_e32 v26, 16, v215
	v_and_b32_e32 v27, 0xffff0000, v215
	v_pk_add_f32 v[22:23], v[22:23], v[28:29]
	v_pk_add_f32 v[24:25], v[24:25], v[26:27]
	s_cbranch_vccnz .LBB0_168
	s_mov_b64 s[36:37], 0
	global_store_dwordx4 v[34:35], v[22:25], off offset:128 nt

; DEVI float lo2f(unsigned u) { return __uint_as_float(u << 16); }
; DEVI float hi2f(unsigned u) { return __uint_as_float(u & 0xffff0000u); }
; DEVI void phase_resid_gemm(const Params& p, const bfu* A, int lda, int nkt, const bfu* wT, int ldb, const float* resid32,
;                            float* ssq_out, float* out32, char* lds) {
;     ...
;       for (int ni = 0; ni < 4; ++ni) {
;         const int n = n0 + wn * 64 + ni * 16 + fq * 4;
;         float4 r;
;         if (resid32) r = *(const float4*)(resid32 + (long)m * 1024 + n);
;         else { const uint2 u = *(const uint2*)(xs + (long)m * LDX + n); r = make_float4(lo2f(u.x), hi2f(u.x), lo2f(u.y), hi2f(u.y)); }
;         float4 o;
;         o.x = r.x + acc[ni][mi][0]; o.y = r.y + acc[ni][mi][1]; o.z = r.z + acc[ni][mi][2]; o.w = r.w + acc[ni][mi][3];
;         if (out32) *(float4*)(out32 + (long)m * 1024 + n) = o;
.LBB0_173:
	global_store_dwordx4 v[34:35], v[18:21], off offset:192 nt
	s_cbranch_execnz .LBB0_172

; DEVI float lo2f(unsigned u) { return __uint_as_float(u << 16); }
; DEVI float hi2f(unsigned u) { return __uint_as_float(u & 0xffff0000u); }
; DEVI void phase_resid_gemm(const Params& p, const bfu* A, int lda, int nkt, const bfu* wT, int ldb, const float* resid32,
;                            float* ssq_out, float* out32, char* lds) {
;     ...
;       for (int ni = 0; ni < 4; ++ni) {
;         const int n = n0 + wn * 64 + ni * 16 + fq * 4;
;         float4 r;
;         if (resid32) r = *(const float4*)(resid32 + (long)m * 1024 + n);
;         else { const uint2 u = *(const uint2*)(xs + (long)m * LDX + n); r = make_float4(lo2f(u.x), hi2f(u.x), lo2f(u.y), hi2f(u.y)); }
;         float4 o;
;         o.x = r.x + acc[ni][mi][0]; o.y = r.y + acc[ni][mi][1]; o.z = r.z + acc[ni][mi][2]; o.w = r.w + acc[ni][mi][3];
;         if (out32) *(float4*)(out32 + (long)m * 1024 + n) = o;
.LBB0_178:
	v_or_b32_e32 v20, 0x70, v132
	s_waitcnt lgkmcnt(0)
	v_mov_b64_e32 v[18:19], s[2:3]
	v_mad_i64_i32 v[18:19], s[28:29], v20, s95, v[18:19]
	v_lshl_add_u64 v[18:19], v[130:131], 1, v[18:19]
	v_lshl_add_u64 v[218:219], v[18:19], 0, v[254:255]
	global_load_dwordx4 v[214:217], v[218:219], off
	v_ashrrev_i32_e32 v21, 31, v20
	v_lshlrev_b64 v[20:21], 12, v[20:21]
	v_lshl_add_u64 v[20:21], s[0:1], 0, v[20:21]
	s_mov_b64 s[36:37], -1
	s_and_b64 vcc, exec, s[42:43]
	v_lshl_add_u64 v[20:21], v[130:131], 2, v[20:21]
	s_waitcnt vmcnt(0)
	v_permlane16_swap_b32_e32 v214, v216
	v_permlane16_swap_b32_e32 v215, v217
	s_nop 1
	v_lshlrev_b32_e32 v24, 16, v214
	v_and_b32_e32 v25, 0xffff0000, v214
	v_lshlrev_b32_e32 v22, 16, v215
	v_and_b32_e32 v23, 0xffff0000, v215
	v_pk_add_f32 v[14:15], v[14:15], v[24:25]
	v_pk_add_f32 v[16:17], v[16:17], v[22:23]
	s_cbranch_vccnz .LBB0_180
	s_mov_b64 s[36:37], 0
	global_store_dwordx4 v[20:21], v[14:17], off nt

; DEVI float lo2f(unsigned u) { return __uint_as_float(u << 16); }
; DEVI float hi2f(unsigned u) { return __uint_as_float(u & 0xffff0000u); }
; DEVI void phase_resid_gemm(const Params& p, const bfu* A, int lda, int nkt, const bfu* wT, int ldb, const float* resid32,
;                            float* ssq_out, float* out32, char* lds) {
;     ...
;       for (int ni = 0; ni < 4; ++ni) {
;         const int n = n0 + wn * 64 + ni * 16 + fq * 4;
;         float4 r;
;         if (resid32) r = *(const float4*)(resid32 + (long)m * 1024 + n);
;         else { const uint2 u = *(const uint2*)(xs + (long)m * LDX + n); r = make_float4(lo2f(u.x), hi2f(u.x), lo2f(u.y), hi2f(u.y)); }
;         float4 o;
;         o.x = r.x + acc[ni][mi][0]; o.y = r.y + acc[ni][mi][1]; o.z = r.z + acc[ni][mi][2]; o.w = r.w + acc[ni][mi][3];
;         if (out32) *(float4*)(out32 + (long)m * 1024 + n) = o;
.LBB0_182:
	s_and_b64 vcc, exec, s[42:43]
	s_mov_b64 s[36:37], -1
	s_waitcnt vmcnt(0)
	v_lshlrev_b32_e32 v16, 16, v216
	v_and_b32_e32 v17, 0xffff0000, v216
	v_lshlrev_b32_e32 v14, 16, v217
	v_and_b32_e32 v15, 0xffff0000, v217
	v_pk_add_f32 v[10:11], v[10:11], v[16:17]
	v_pk_add_f32 v[12:13], v[12:13], v[14:15]
	s_cbranch_vccnz .LBB0_184
	s_mov_b64 s[36:37], 0
	global_store_dwordx4 v[20:21], v[10:13], off offset:64 nt

; DEVI float lo2f(unsigned u) { return __uint_as_float(u << 16); }
; DEVI float hi2f(unsigned u) { return __uint_as_float(u & 0xffff0000u); }
; DEVI void phase_resid_gemm(const Params& p, const bfu* A, int lda, int nkt, const bfu* wT, int ldb, const float* resid32,
;                            float* ssq_out, float* out32, char* lds) {
;     ...
;       for (int ni = 0; ni < 4; ++ni) {
;         const int n = n0 + wn * 64 + ni * 16 + fq * 4;
;         float4 r;
;         if (resid32) r = *(const float4*)(resid32 + (long)m * 1024 + n);
;         else { const uint2 u = *(const uint2*)(xs + (long)m * LDX + n); r = make_float4(lo2f(u.x), hi2f(u.x), lo2f(u.y), hi2f(u.y)); }
;         float4 o;
;         o.x = r.x + acc[ni][mi][0]; o.y = r.y + acc[ni][mi][1]; o.z = r.z + acc[ni][mi][2]; o.w = r.w + acc[ni][mi][3];
;         if (out32) *(float4*)(out32 + (long)m * 1024 + n) = o;
.LBB0_186:
	v_lshl_add_u64 v[218:219], v[18:19], 0, v[254:255]
	global_load_dwordx4 v[214:217], v[218:219], off offset:64
	s_and_b64 vcc, exec, s[42:43]
	s_mov_b64 s[36:37], -1
	s_waitcnt vmcnt(0)
	v_permlane16_swap_b32_e32 v214, v216
	v_permlane16_swap_b32_e32 v215, v217
	s_nop 1
	v_lshlrev_b32_e32 v12, 16, v214
	v_and_b32_e32 v13, 0xffff0000, v214
	v_lshlrev_b32_e32 v10, 16, v215
	v_and_b32_e32 v11, 0xffff0000, v215
	v_pk_add_f32 v[6:7], v[6:7], v[12:13]
	v_pk_add_f32 v[8:9], v[8:9], v[10:11]
	s_cbranch_vccnz .LBB0_188
	s_mov_b64 s[36:37], 0
	global_store_dwordx4 v[20:21], v[6:9], off offset:128 nt

; DEVI float lo2f(unsigned u) { return __uint_as_float(u << 16); }
; DEVI float hi2f(unsigned u) { return __uint_as_float(u & 0xffff0000u); }
; DEVI void phase_resid_gemm(const Params& p, const bfu* A, int lda, int nkt, const bfu* wT, int ldb, const float* resid32,
;                            float* ssq_out, float* out32, char* lds) {
;     ...
;       for (int ni = 0; ni < 4; ++ni) {
;         const int n = n0 + wn * 64 + ni * 16 + fq * 4;
;         float4 r;
;         if (resid32) r = *(const float4*)(resid32 + (long)m * 1024 + n);
;         else { const uint2 u = *(const uint2*)(xs + (long)m * LDX + n); r = make_float4(lo2f(u.x), hi2f(u.x), lo2f(u.y), hi2f(u.y)); }
;         float4 o;
;         o.x = r.x + acc[ni][mi][0]; o.y = r.y + acc[ni][mi][1]; o.z = r.z + acc[ni][mi][2]; o.w = r.w + acc[ni][mi][3];
;         if (out32) *(float4*)(out32 + (long)m * 1024 + n) = o;
.LBB0_193:
	global_store_dwordx4 v[20:21], v[2:5], off offset:192 nt
	s_cbranch_execnz .LBB0_192

; DEVI float lo2f(unsigned u) { return __uint_as_float(u << 16); }
; DEVI float hi2f(unsigned u) { return __uint_as_float(u & 0xffff0000u); }
; DEVI void phase_resid_gemm(const Params& p, const bfu* A, int lda, int nkt, const bfu* wT, int ldb, const float* resid32,
;                            float* ssq_out, float* out32, char* lds) {
;     ...
;         float4 r;
;         if (resid32) r = *(const float4*)(resid32 + (long)m * 1024 + n);
;         else { const uint2 u = *(const uint2*)(xs + (long)m * LDX + n); r = make_float4(lo2f(u.x), hi2f(u.x), lo2f(u.y), hi2f(u.y)); }
;         float4 o;
;         o.x = r.x + acc[ni][mi][0]; o.y = r.y + acc[ni][mi][1]; o.z = r.z + acc[ni][mi][2]; o.w = r.w + acc[ni][mi][3];
;         if (out32) *(float4*)(out32 + (long)m * 1024 + n) = o;
;         else {
;           uint2 ob; ob.x = pack2(o.x, o.y); ob.y = pack2(o.z, o.w);
;           *(uint2*)(xs + (long)m * LDX + n) = ob;
;           const float q0 = lo2f(ob.x), q1 = hi2f(ob.x), q2 = lo2f(ob.y), q3 = hi2f(ob.y);
;           ss += q0 * q0 + q1 * q1 + q2 * q2 + q3 * q3;
.LBB0_250:
	s_waitcnt vmcnt(0)
	v_pk_add_f32 v[126:127], v[162:163], v[126:127]
	v_pk_add_f32 v[128:129], v[164:165], v[128:129]
	v_cvt_pk_bf16_f32 v138, v126, v127
	v_cvt_pk_bf16_f32 v139, v128, v129
	s_and_b64 vcc, exec, s[40:41]
	v_mov_b32_e32 v200, v138
	v_mov_b32_e32 v201, v139
	s_cbranch_vccnz .LBB0_263
	global_load_dwordx4 v[126:129], v[136:137], off offset:64 nt
	s_cbranch_execnz .LBB0_253

; DEVI float lo2f(unsigned u) { return __uint_as_float(u << 16); }
; DEVI float hi2f(unsigned u) { return __uint_as_float(u & 0xffff0000u); }
; DEVI void phase_resid_gemm(const Params& p, const bfu* A, int lda, int nkt, const bfu* wT, int ldb, const float* resid32,
;                            float* ssq_out, float* out32, char* lds) {
;     ...
;         float4 r;
;         if (resid32) r = *(const float4*)(resid32 + (long)m * 1024 + n);
;         else { const uint2 u = *(const uint2*)(xs + (long)m * LDX + n); r = make_float4(lo2f(u.x), hi2f(u.x), lo2f(u.y), hi2f(u.y)); }
;         float4 o;
;         o.x = r.x + acc[ni][mi][0]; o.y = r.y + acc[ni][mi][1]; o.z = r.z + acc[ni][mi][2]; o.w = r.w + acc[ni][mi][3];
;         if (out32) *(float4*)(out32 + (long)m * 1024 + n) = o;
;         else {
;           uint2 ob; ob.x = pack2(o.x, o.y); ob.y = pack2(o.z, o.w);
;           *(uint2*)(xs + (long)m * LDX + n) = ob;
;           const float q0 = lo2f(ob.x), q1 = hi2f(ob.x), q2 = lo2f(ob.y), q3 = hi2f(ob.y);
;           ss += q0 * q0 + q1 * q1 + q2 * q2 + q3 * q3;
.LBB0_253:
	s_waitcnt vmcnt(0)
	v_pk_add_f32 v[122:123], v[122:123], v[126:127]
	v_pk_add_f32 v[124:125], v[124:125], v[128:129]
	v_cvt_pk_bf16_f32 v126, v122, v123
	v_cvt_pk_bf16_f32 v127, v124, v125
	s_and_b64 vcc, exec, s[40:41]
	v_mov_b32_e32 v206, v126
	v_mov_b32_e32 v207, v127
	v_mov_b32_e32 v204, v200
	v_mov_b32_e32 v205, v201
	v_lshl_add_u64 v[212:213], v[134:135], 0, v[254:255]
	s_nop 0
	v_permlane16_swap_b32_e32 v204, v206
	v_permlane16_swap_b32_e32 v205, v207
	s_nop 1
	global_store_dwordx4 v[212:213], v[204:207], off
	s_cbranch_vccnz .LBB0_264
	global_load_dwordx4 v[122:125], v[136:137], off offset:128 nt
	s_cbranch_execnz .LBB0_256

; DEVI float lo2f(unsigned u) { return __uint_as_float(u << 16); }
; DEVI float hi2f(unsigned u) { return __uint_as_float(u & 0xffff0000u); }
; DEVI void phase_resid_gemm(const Params& p, const bfu* A, int lda, int nkt, const bfu* wT, int ldb, const float* resid32,
;                            float* ssq_out, float* out32, char* lds) {
;     ...
;         float4 r;
;         if (resid32) r = *(const float4*)(resid32 + (long)m * 1024 + n);
;         else { const uint2 u = *(const uint2*)(xs + (long)m * LDX + n); r = make_float4(lo2f(u.x), hi2f(u.x), lo2f(u.y), hi2f(u.y)); }
;         float4 o;
;         o.x = r.x + acc[ni][mi][0]; o.y = r.y + acc[ni][mi][1]; o.z = r.z + acc[ni][mi][2]; o.w = r.w + acc[ni][mi][3];
;         if (out32) *(float4*)(out32 + (long)m * 1024 + n) = o;
;         else {
;           uint2 ob; ob.x = pack2(o.x, o.y); ob.y = pack2(o.z, o.w);
;           *(uint2*)(xs + (long)m * LDX + n) = ob;
;           const float q0 = lo2f(ob.x), q1 = hi2f(ob.x), q2 = lo2f(ob.y), q3 = hi2f(ob.y);
;           ss += q0 * q0 + q1 * q1 + q2 * q2 + q3 * q3;
.LBB0_256:
	s_waitcnt vmcnt(0)
	v_pk_add_f32 v[118:119], v[118:119], v[122:123]
	v_pk_add_f32 v[120:121], v[120:121], v[124:125]
	v_cvt_pk_bf16_f32 v122, v118, v119
	v_cvt_pk_bf16_f32 v123, v120, v121
	s_and_b64 vcc, exec, s[40:41]
	v_mov_b32_e32 v200, v122
	v_mov_b32_e32 v201, v123
	s_cbranch_vccnz .LBB0_265
	global_load_dwordx4 v[118:121], v[136:137], off offset:192 nt
	s_cbranch_execnz .LBB0_259

; DEVI float lo2f(unsigned u) { return __uint_as_float(u << 16); }
; DEVI float hi2f(unsigned u) { return __uint_as_float(u & 0xffff0000u); }
; DEVI void phase_resid_gemm(const Params& p, const bfu* A, int lda, int nkt, const bfu* wT, int ldb, const float* resid32,
;                            float* ssq_out, float* out32, char* lds) {
;     ...
;         float4 r;
;         if (resid32) r = *(const float4*)(resid32 + (long)m * 1024 + n);
;         else { const uint2 u = *(const uint2*)(xs + (long)m * LDX + n); r = make_float4(lo2f(u.x), hi2f(u.x), lo2f(u.y), hi2f(u.y)); }
;         float4 o;
;         o.x = r.x + acc[ni][mi][0]; o.y = r.y + acc[ni][mi][1]; o.z = r.z + acc[ni][mi][2]; o.w = r.w + acc[ni][mi][3];
;         if (out32) *(float4*)(out32 + (long)m * 1024 + n) = o;
;         else {
;           uint2 ob; ob.x = pack2(o.x, o.y); ob.y = pack2(o.z, o.w);
;           *(uint2*)(xs + (long)m * LDX + n) = ob;
;           const float q0 = lo2f(ob.x), q1 = hi2f(ob.x), q2 = lo2f(ob.y), q3 = hi2f(ob.y);
;           ss += q0 * q0 + q1 * q1 + q2 * q2 + q3 * q3;
.LBB0_261:
	s_or_b64 exec, exec, s[36:37]
	v_or_b32_e32 v118, 16, v132
	v_ashrrev_i32_e32 v119, 31, v118
	s_waitcnt lgkmcnt(0)
	v_lshlrev_b64 v[110:111], 12, v[118:119]
	v_lshl_add_u64 v[110:111], s[0:1], 0, v[110:111]
	s_and_b64 vcc, exec, s[40:41]
	v_lshl_add_u64 v[120:121], v[130:131], 2, v[110:111]
	s_cbranch_vccnz .LBB0_266
	global_load_dwordx4 v[110:113], v[120:121], off nt
	s_mov_b64 s[36:37], 0
	s_branch .LBB0_267

; DEVI float lo2f(unsigned u) { return __uint_as_float(u << 16); }
; DEVI float hi2f(unsigned u) { return __uint_as_float(u & 0xffff0000u); }
; DEVI void phase_resid_gemm(const Params& p, const bfu* A, int lda, int nkt, const bfu* wT, int ldb, const float* resid32,
;                            float* ssq_out, float* out32, char* lds) {
;     ...
;         float4 r;
;         if (resid32) r = *(const float4*)(resid32 + (long)m * 1024 + n);
;         else { const uint2 u = *(const uint2*)(xs + (long)m * LDX + n); r = make_float4(lo2f(u.x), hi2f(u.x), lo2f(u.y), hi2f(u.y)); }
;         float4 o;
;         o.x = r.x + acc[ni][mi][0]; o.y = r.y + acc[ni][mi][1]; o.z = r.z + acc[ni][mi][2]; o.w = r.w + acc[ni][mi][3];
;         if (out32) *(float4*)(out32 + (long)m * 1024 + n) = o;
;         else {
;           uint2 ob; ob.x = pack2(o.x, o.y); ob.y = pack2(o.z, o.w);
;           *(uint2*)(xs + (long)m * LDX + n) = ob;
;           const float q0 = lo2f(ob.x), q1 = hi2f(ob.x), q2 = lo2f(ob.y), q3 = hi2f(ob.y);
;           ss += q0 * q0 + q1 * q1 + q2 * q2 + q3 * q3;
.LBB0_269:
	s_waitcnt vmcnt(0)
	v_pk_add_f32 v[110:111], v[114:115], v[110:111]
	v_pk_add_f32 v[112:113], v[116:117], v[112:113]
	v_cvt_pk_bf16_f32 v114, v110, v111
	v_cvt_pk_bf16_f32 v115, v112, v113
	s_and_b64 vcc, exec, s[40:41]
	v_mov_b32_e32 v200, v114
	v_mov_b32_e32 v201, v115
	s_cbranch_vccnz .LBB0_282
	global_load_dwordx4 v[110:113], v[120:121], off offset:64 nt
	s_cbranch_execnz .LBB0_272

; DEVI float lo2f(unsigned u) { return __uint_as_float(u << 16); }
; DEVI float hi2f(unsigned u) { return __uint_as_float(u & 0xffff0000u); }
; DEVI void phase_resid_gemm(const Params& p, const bfu* A, int lda, int nkt, const bfu* wT, int ldb, const float* resid32,
;                            float* ssq_out, float* out32, char* lds) {
;     ...
;         float4 r;
;         if (resid32) r = *(const float4*)(resid32 + (long)m * 1024 + n);
;         else { const uint2 u = *(const uint2*)(xs + (long)m * LDX + n); r = make_float4(lo2f(u.x), hi2f(u.x), lo2f(u.y), hi2f(u.y)); }
;         float4 o;
;         o.x = r.x + acc[ni][mi][0]; o.y = r.y + acc[ni][mi][1]; o.z = r.z + acc[ni][mi][2]; o.w = r.w + acc[ni][mi][3];
;         if (out32) *(float4*)(out32 + (long)m * 1024 + n) = o;
;         else {
;           uint2 ob; ob.x = pack2(o.x, o.y); ob.y = pack2(o.z, o.w);
;           *(uint2*)(xs + (long)m * LDX + n) = ob;
;           const float q0 = lo2f(ob.x), q1 = hi2f(ob.x), q2 = lo2f(ob.y), q3 = hi2f(ob.y);
;           ss += q0 * q0 + q1 * q1 + q2 * q2 + q3 * q3;
.LBB0_272:
	s_waitcnt vmcnt(0)
	v_pk_add_f32 v[106:107], v[106:107], v[110:111]
	v_pk_add_f32 v[108:109], v[108:109], v[112:113]
	v_cvt_pk_bf16_f32 v110, v106, v107
	v_cvt_pk_bf16_f32 v111, v108, v109
	s_and_b64 vcc, exec, s[40:41]
	v_mov_b32_e32 v206, v110
	v_mov_b32_e32 v207, v111
	v_mov_b32_e32 v204, v200
	v_mov_b32_e32 v205, v201
	v_lshl_add_u64 v[212:213], v[118:119], 0, v[254:255]
	s_nop 0
	v_permlane16_swap_b32_e32 v204, v206
	v_permlane16_swap_b32_e32 v205, v207
	s_nop 1
	global_store_dwordx4 v[212:213], v[204:207], off
	s_cbranch_vccnz .LBB0_283
	global_load_dwordx4 v[106:109], v[120:121], off offset:128 nt
	s_cbranch_execnz .LBB0_275

; DEVI float lo2f(unsigned u) { return __uint_as_float(u << 16); }
; DEVI float hi2f(unsigned u) { return __uint_as_float(u & 0xffff0000u); }
; DEVI void phase_resid_gemm(const Params& p, const bfu* A, int lda, int nkt, const bfu* wT, int ldb, const float* resid32,
;                            float* ssq_out, float* out32, char* lds) {
;     ...
;         float4 r;
;         if (resid32) r = *(const float4*)(resid32 + (long)m * 1024 + n);
;         else { const uint2 u = *(const uint2*)(xs + (long)m * LDX + n); r = make_float4(lo2f(u.x), hi2f(u.x), lo2f(u.y), hi2f(u.y)); }
;         float4 o;
;         o.x = r.x + acc[ni][mi][0]; o.y = r.y + acc[ni][mi][1]; o.z = r.z + acc[ni][mi][2]; o.w = r.w + acc[ni][mi][3];
;         if (out32) *(float4*)(out32 + (long)m * 1024 + n) = o;
;         else {
;           uint2 ob; ob.x = pack2(o.x, o.y); ob.y = pack2(o.z, o.w);
;           *(uint2*)(xs + (long)m * LDX + n) = ob;
;           const float q0 = lo2f(ob.x), q1 = hi2f(ob.x), q2 = lo2f(ob.y), q3 = hi2f(ob.y);
;           ss += q0 * q0 + q1 * q1 + q2 * q2 + q3 * q3;
.LBB0_275:
	s_waitcnt vmcnt(0)
	v_pk_add_f32 v[102:103], v[102:103], v[106:107]
	v_pk_add_f32 v[104:105], v[104:105], v[108:109]
	v_cvt_pk_bf16_f32 v106, v102, v103
	v_cvt_pk_bf16_f32 v107, v104, v105
	s_and_b64 vcc, exec, s[40:41]
	v_mov_b32_e32 v200, v106
	v_mov_b32_e32 v201, v107
	s_cbranch_vccnz .LBB0_284
	global_load_dwordx4 v[102:105], v[120:121], off offset:192 nt
	s_cbranch_execnz .LBB0_278

; DEVI float lo2f(unsigned u) { return __uint_as_float(u << 16); }
; DEVI float hi2f(unsigned u) { return __uint_as_float(u & 0xffff0000u); }
; DEVI void phase_resid_gemm(const Params& p, const bfu* A, int lda, int nkt, const bfu* wT, int ldb, const float* resid32,
;                            float* ssq_out, float* out32, char* lds) {
;     ...
;         float4 r;
;         if (resid32) r = *(const float4*)(resid32 + (long)m * 1024 + n);
;         else { const uint2 u = *(const uint2*)(xs + (long)m * LDX + n); r = make_float4(lo2f(u.x), hi2f(u.x), lo2f(u.y), hi2f(u.y)); }
;         float4 o;
;         o.x = r.x + acc[ni][mi][0]; o.y = r.y + acc[ni][mi][1]; o.z = r.z + acc[ni][mi][2]; o.w = r.w + acc[ni][mi][3];
;         if (out32) *(float4*)(out32 + (long)m * 1024 + n) = o;
;         else {
;           uint2 ob; ob.x = pack2(o.x, o.y); ob.y = pack2(o.z, o.w);
;           *(uint2*)(xs + (long)m * LDX + n) = ob;
;           const float q0 = lo2f(ob.x), q1 = hi2f(ob.x), q2 = lo2f(ob.y), q3 = hi2f(ob.y);
;           ss += q0 * q0 + q1 * q1 + q2 * q2 + q3 * q3;
.LBB0_280:
	s_or_b64 exec, exec, s[36:37]
	v_or_b32_e32 v102, 32, v132
	v_ashrrev_i32_e32 v103, 31, v102
	s_waitcnt lgkmcnt(0)
	v_lshlrev_b64 v[94:95], 12, v[102:103]
	v_lshl_add_u64 v[94:95], s[0:1], 0, v[94:95]
	s_and_b64 vcc, exec, s[40:41]
	v_lshl_add_u64 v[104:105], v[130:131], 2, v[94:95]
	s_cbranch_vccnz .LBB0_285
	global_load_dwordx4 v[94:97], v[104:105], off nt
	s_mov_b64 s[36:37], 0
	s_branch .LBB0_286

; DEVI float lo2f(unsigned u) { return __uint_as_float(u << 16); }
; DEVI float hi2f(unsigned u) { return __uint_as_float(u & 0xffff0000u); }
; DEVI void phase_resid_gemm(const Params& p, const bfu* A, int lda, int nkt, const bfu* wT, int ldb, const float* resid32,
;                            float* ssq_out, float* out32, char* lds) {
;     ...
;         float4 r;
;         if (resid32) r = *(const float4*)(resid32 + (long)m * 1024 + n);
;         else { const uint2 u = *(const uint2*)(xs + (long)m * LDX + n); r = make_float4(lo2f(u.x), hi2f(u.x), lo2f(u.y), hi2f(u.y)); }
;         float4 o;
;         o.x = r.x + acc[ni][mi][0]; o.y = r.y + acc[ni][mi][1]; o.z = r.z + acc[ni][mi][2]; o.w = r.w + acc[ni][mi][3];
;         if (out32) *(float4*)(out32 + (long)m * 1024 + n) = o;
;         else {
;           uint2 ob; ob.x = pack2(o.x, o.y); ob.y = pack2(o.z, o.w);
;           *(uint2*)(xs + (long)m * LDX + n) = ob;
;           const float q0 = lo2f(ob.x), q1 = hi2f(ob.x), q2 = lo2f(ob.y), q3 = hi2f(ob.y);
;           ss += q0 * q0 + q1 * q1 + q2 * q2 + q3 * q3;
.LBB0_288:
	s_waitcnt vmcnt(0)
	v_pk_add_f32 v[94:95], v[98:99], v[94:95]
	v_pk_add_f32 v[96:97], v[100:101], v[96:97]
	v_cvt_pk_bf16_f32 v98, v94, v95
	v_cvt_pk_bf16_f32 v99, v96, v97
	s_and_b64 vcc, exec, s[40:41]
	v_mov_b32_e32 v200, v98
	v_mov_b32_e32 v201, v99
	s_cbranch_vccnz .LBB0_301
	global_load_dwordx4 v[94:97], v[104:105], off offset:64 nt
	s_cbranch_execnz .LBB0_291

; DEVI float lo2f(unsigned u) { return __uint_as_float(u << 16); }
; DEVI float hi2f(unsigned u) { return __uint_as_float(u & 0xffff0000u); }
; DEVI void phase_resid_gemm(const Params& p, const bfu* A, int lda, int nkt, const bfu* wT, int ldb, const float* resid32,
;                            float* ssq_out, float* out32, char* lds) {
;     ...
;         float4 r;
;         if (resid32) r = *(const float4*)(resid32 + (long)m * 1024 + n);
;         else { const uint2 u = *(const uint2*)(xs + (long)m * LDX + n); r = make_float4(lo2f(u.x), hi2f(u.x), lo2f(u.y), hi2f(u.y)); }
;         float4 o;
;         o.x = r.x + acc[ni][mi][0]; o.y = r.y + acc[ni][mi][1]; o.z = r.z + acc[ni][mi][2]; o.w = r.w + acc[ni][mi][3];
;         if (out32) *(float4*)(out32 + (long)m * 1024 + n) = o;
;         else {
;           uint2 ob; ob.x = pack2(o.x, o.y); ob.y = pack2(o.z, o.w);
;           *(uint2*)(xs + (long)m * LDX + n) = ob;
;           const float q0 = lo2f(ob.x), q1 = hi2f(ob.x), q2 = lo2f(ob.y), q3 = hi2f(ob.y);
;           ss += q0 * q0 + q1 * q1 + q2 * q2 + q3 * q3;
.LBB0_291:
	s_waitcnt vmcnt(0)
	v_pk_add_f32 v[90:91], v[90:91], v[94:95]
	v_pk_add_f32 v[92:93], v[92:93], v[96:97]
	v_cvt_pk_bf16_f32 v94, v90, v91
	v_cvt_pk_bf16_f32 v95, v92, v93
	s_and_b64 vcc, exec, s[40:41]
	v_mov_b32_e32 v206, v94
	v_mov_b32_e32 v207, v95
	v_mov_b32_e32 v204, v200
	v_mov_b32_e32 v205, v201
	v_lshl_add_u64 v[212:213], v[102:103], 0, v[254:255]
	s_nop 0
	v_permlane16_swap_b32_e32 v204, v206
	v_permlane16_swap_b32_e32 v205, v207
	s_nop 1
	global_store_dwordx4 v[212:213], v[204:207], off
	s_cbranch_vccnz .LBB0_302
	global_load_dwordx4 v[90:93], v[104:105], off offset:128 nt
	s_cbranch_execnz .LBB0_294

; DEVI float lo2f(unsigned u) { return __uint_as_float(u << 16); }
; DEVI float hi2f(unsigned u) { return __uint_as_float(u & 0xffff0000u); }
; DEVI void phase_resid_gemm(const Params& p, const bfu* A, int lda, int nkt, const bfu* wT, int ldb, const float* resid32,
;                            float* ssq_out, float* out32, char* lds) {
;     ...
;         float4 r;
;         if (resid32) r = *(const float4*)(resid32 + (long)m * 1024 + n);
;         else { const uint2 u = *(const uint2*)(xs + (long)m * LDX + n); r = make_float4(lo2f(u.x), hi2f(u.x), lo2f(u.y), hi2f(u.y)); }
;         float4 o;
;         o.x = r.x + acc[ni][mi][0]; o.y = r.y + acc[ni][mi][1]; o.z = r.z + acc[ni][mi][2]; o.w = r.w + acc[ni][mi][3];
;         if (out32) *(float4*)(out32 + (long)m * 1024 + n) = o;
;         else {
;           uint2 ob; ob.x = pack2(o.x, o.y); ob.y = pack2(o.z, o.w);
;           *(uint2*)(xs + (long)m * LDX + n) = ob;
;           const float q0 = lo2f(ob.x), q1 = hi2f(ob.x), q2 = lo2f(ob.y), q3 = hi2f(ob.y);
;           ss += q0 * q0 + q1 * q1 + q2 * q2 + q3 * q3;
.LBB0_294:
	s_waitcnt vmcnt(0)
	v_pk_add_f32 v[86:87], v[86:87], v[90:91]
	v_pk_add_f32 v[88:89], v[88:89], v[92:93]
	v_cvt_pk_bf16_f32 v90, v86, v87
	v_cvt_pk_bf16_f32 v91, v88, v89
	s_and_b64 vcc, exec, s[40:41]
	v_mov_b32_e32 v200, v90
	v_mov_b32_e32 v201, v91
	s_cbranch_vccnz .LBB0_303
	global_load_dwordx4 v[86:89], v[104:105], off offset:192 nt
	s_cbranch_execnz .LBB0_297

; DEVI float lo2f(unsigned u) { return __uint_as_float(u << 16); }
; DEVI float hi2f(unsigned u) { return __uint_as_float(u & 0xffff0000u); }
; DEVI void phase_resid_gemm(const Params& p, const bfu* A, int lda, int nkt, const bfu* wT, int ldb, const float* resid32,
;                            float* ssq_out, float* out32, char* lds) {
;     ...
;     for (int mi = 0; mi < 8; ++mi) {
;       const int m = m0 + wm * 128 + mi * 16 + fr;
;       float ss = 0.f;
; #pragma unroll
;       for (int ni = 0; ni < 4; ++ni) {
;         const int n = n0 + wn * 64 + ni * 16 + fq * 4;
;         float4 r;
;         if (resid32) r = *(const float4*)(resid32 + (long)m * 1024 + n);
;         else { const uint2 u = *(const uint2*)(xs + (long)m * LDX + n); r = make_float4(lo2f(u.x), hi2f(u.x), lo2f(u.y), hi2f(u.y)); }
;         float4 o;
;         o.x = r.x + acc[ni][mi][0]; o.y = r.y + acc[ni][mi][1]; o.z = r.z + acc[ni][mi][2]; o.w = r.w + acc[ni][mi][3];
.LBB0_299:
	s_or_b64 exec, exec, s[36:37]
	v_or_b32_e32 v86, 48, v132
	v_ashrrev_i32_e32 v87, 31, v86
	s_waitcnt lgkmcnt(0)
	v_lshlrev_b64 v[78:79], 12, v[86:87]
	v_lshl_add_u64 v[78:79], s[0:1], 0, v[78:79]
	s_and_b64 vcc, exec, s[40:41]
	v_lshl_add_u64 v[88:89], v[130:131], 2, v[78:79]
	s_cbranch_vccnz .LBB0_304
	global_load_dwordx4 v[78:81], v[88:89], off nt
	s_mov_b64 s[36:37], 0
	s_branch .LBB0_305

; DEVI float lo2f(unsigned u) { return __uint_as_float(u << 16); }
; DEVI float hi2f(unsigned u) { return __uint_as_float(u & 0xffff0000u); }
; DEVI void phase_resid_gemm(const Params& p, const bfu* A, int lda, int nkt, const bfu* wT, int ldb, const float* resid32,
;                            float* ssq_out, float* out32, char* lds) {
;     ...
;       for (int ni = 0; ni < 4; ++ni) {
;         const int n = n0 + wn * 64 + ni * 16 + fq * 4;
;         float4 r;
;         if (resid32) r = *(const float4*)(resid32 + (long)m * 1024 + n);
;         else { const uint2 u = *(const uint2*)(xs + (long)m * LDX + n); r = make_float4(lo2f(u.x), hi2f(u.x), lo2f(u.y), hi2f(u.y)); }
;         float4 o;
;         o.x = r.x + acc[ni][mi][0]; o.y = r.y + acc[ni][mi][1]; o.z = r.z + acc[ni][mi][2]; o.w = r.w + acc[ni][mi][3];
;         if (out32) *(float4*)(out32 + (long)m * 1024 + n) = o;
;         else {
;           uint2 ob; ob.x = pack2(o.x, o.y); ob.y = pack2(o.z, o.w);
;           *(uint2*)(xs + (long)m * LDX + n) = ob;
.LBB0_307:
	s_waitcnt vmcnt(0)
	v_pk_add_f32 v[78:79], v[82:83], v[78:79]
	v_pk_add_f32 v[80:81], v[84:85], v[80:81]
	v_cvt_pk_bf16_f32 v82, v78, v79
	v_cvt_pk_bf16_f32 v83, v80, v81
	s_and_b64 vcc, exec, s[40:41]
	v_mov_b32_e32 v200, v82
	v_mov_b32_e32 v201, v83
	s_cbranch_vccnz .LBB0_320
	global_load_dwordx4 v[78:81], v[88:89], off offset:64 nt
	s_cbranch_execnz .LBB0_310

; DEVI float lo2f(unsigned u) { return __uint_as_float(u << 16); }
; DEVI float hi2f(unsigned u) { return __uint_as_float(u & 0xffff0000u); }
; DEVI void phase_resid_gemm(const Params& p, const bfu* A, int lda, int nkt, const bfu* wT, int ldb, const float* resid32,
;                            float* ssq_out, float* out32, char* lds) {
;     ...
;       for (int ni = 0; ni < 4; ++ni) {
;         const int n = n0 + wn * 64 + ni * 16 + fq * 4;
;         float4 r;
;         if (resid32) r = *(const float4*)(resid32 + (long)m * 1024 + n);
;         else { const uint2 u = *(const uint2*)(xs + (long)m * LDX + n); r = make_float4(lo2f(u.x), hi2f(u.x), lo2f(u.y), hi2f(u.y)); }
;         float4 o;
;         o.x = r.x + acc[ni][mi][0]; o.y = r.y + acc[ni][mi][1]; o.z = r.z + acc[ni][mi][2]; o.w = r.w + acc[ni][mi][3];
;         if (out32) *(float4*)(out32 + (long)m * 1024 + n) = o;
;         else {
;           uint2 ob; ob.x = pack2(o.x, o.y); ob.y = pack2(o.z, o.w);
;           *(uint2*)(xs + (long)m * LDX + n) = ob;
.LBB0_310:
	s_waitcnt vmcnt(0)
	v_pk_add_f32 v[74:75], v[74:75], v[78:79]
	v_pk_add_f32 v[76:77], v[76:77], v[80:81]
	v_cvt_pk_bf16_f32 v78, v74, v75
	v_cvt_pk_bf16_f32 v79, v76, v77
	s_and_b64 vcc, exec, s[40:41]
	v_mov_b32_e32 v206, v78
	v_mov_b32_e32 v207, v79
	v_mov_b32_e32 v204, v200
	v_mov_b32_e32 v205, v201
	v_lshl_add_u64 v[212:213], v[86:87], 0, v[254:255]
	s_nop 0
	v_permlane16_swap_b32_e32 v204, v206
	v_permlane16_swap_b32_e32 v205, v207
	s_nop 1
	global_store_dwordx4 v[212:213], v[204:207], off
	s_cbranch_vccnz .LBB0_321
	global_load_dwordx4 v[74:77], v[88:89], off offset:128 nt
	s_cbranch_execnz .LBB0_313

; DEVI float lo2f(unsigned u) { return __uint_as_float(u << 16); }
; DEVI float hi2f(unsigned u) { return __uint_as_float(u & 0xffff0000u); }
; DEVI void phase_resid_gemm(const Params& p, const bfu* A, int lda, int nkt, const bfu* wT, int ldb, const float* resid32,
;                            float* ssq_out, float* out32, char* lds) {
;     ...
;       for (int ni = 0; ni < 4; ++ni) {
;         const int n = n0 + wn * 64 + ni * 16 + fq * 4;
;         float4 r;
;         if (resid32) r = *(const float4*)(resid32 + (long)m * 1024 + n);
;         else { const uint2 u = *(const uint2*)(xs + (long)m * LDX + n); r = make_float4(lo2f(u.x), hi2f(u.x), lo2f(u.y), hi2f(u.y)); }
;         float4 o;
;         o.x = r.x + acc[ni][mi][0]; o.y = r.y + acc[ni][mi][1]; o.z = r.z + acc[ni][mi][2]; o.w = r.w + acc[ni][mi][3];
;         if (out32) *(float4*)(out32 + (long)m * 1024 + n) = o;
;         else {
;           uint2 ob; ob.x = pack2(o.x, o.y); ob.y = pack2(o.z, o.w);
;           *(uint2*)(xs + (long)m * LDX + n) = ob;
.LBB0_313:
	s_waitcnt vmcnt(0)
	v_pk_add_f32 v[70:71], v[70:71], v[74:75]
	v_pk_add_f32 v[72:73], v[72:73], v[76:77]
	v_cvt_pk_bf16_f32 v74, v70, v71
	v_cvt_pk_bf16_f32 v75, v72, v73
	s_and_b64 vcc, exec, s[40:41]
	v_mov_b32_e32 v200, v74
	v_mov_b32_e32 v201, v75
	s_cbranch_vccnz .LBB0_322
	global_load_dwordx4 v[70:73], v[88:89], off offset:192 nt
	s_cbranch_execnz .LBB0_316

; DEVI float lo2f(unsigned u) { return __uint_as_float(u << 16); }
; DEVI float hi2f(unsigned u) { return __uint_as_float(u & 0xffff0000u); }
; DEVI void phase_resid_gemm(const Params& p, const bfu* A, int lda, int nkt, const bfu* wT, int ldb, const float* resid32,
;                            float* ssq_out, float* out32, char* lds) {
;     ...
;     for (int mi = 0; mi < 8; ++mi) {
;       const int m = m0 + wm * 128 + mi * 16 + fr;
;       float ss = 0.f;
; #pragma unroll
;       for (int ni = 0; ni < 4; ++ni) {
;         const int n = n0 + wn * 64 + ni * 16 + fq * 4;
;         float4 r;
;         if (resid32) r = *(const float4*)(resid32 + (long)m * 1024 + n);
;         else { const uint2 u = *(const uint2*)(xs + (long)m * LDX + n); r = make_float4(lo2f(u.x), hi2f(u.x), lo2f(u.y), hi2f(u.y)); }
;         float4 o;
;         o.x = r.x + acc[ni][mi][0]; o.y = r.y + acc[ni][mi][1]; o.z = r.z + acc[ni][mi][2]; o.w = r.w + acc[ni][mi][3];
.LBB0_318:
	s_or_b64 exec, exec, s[36:37]
	v_or_b32_e32 v70, 64, v132
	v_ashrrev_i32_e32 v71, 31, v70
	s_waitcnt lgkmcnt(0)
	v_lshlrev_b64 v[62:63], 12, v[70:71]
	v_lshl_add_u64 v[62:63], s[0:1], 0, v[62:63]
	s_and_b64 vcc, exec, s[40:41]
	v_lshl_add_u64 v[72:73], v[130:131], 2, v[62:63]
	s_cbranch_vccnz .LBB0_323
	global_load_dwordx4 v[62:65], v[72:73], off nt
	s_mov_b64 s[36:37], 0
	s_branch .LBB0_324

; DEVI float lo2f(unsigned u) { return __uint_as_float(u << 16); }
; DEVI float hi2f(unsigned u) { return __uint_as_float(u & 0xffff0000u); }
; DEVI void phase_resid_gemm(const Params& p, const bfu* A, int lda, int nkt, const bfu* wT, int ldb, const float* resid32,
;                            float* ssq_out, float* out32, char* lds) {
;     ...
;       for (int ni = 0; ni < 4; ++ni) {
;         const int n = n0 + wn * 64 + ni * 16 + fq * 4;
;         float4 r;
;         if (resid32) r = *(const float4*)(resid32 + (long)m * 1024 + n);
;         else { const uint2 u = *(const uint2*)(xs + (long)m * LDX + n); r = make_float4(lo2f(u.x), hi2f(u.x), lo2f(u.y), hi2f(u.y)); }
;         float4 o;
;         o.x = r.x + acc[ni][mi][0]; o.y = r.y + acc[ni][mi][1]; o.z = r.z + acc[ni][mi][2]; o.w = r.w + acc[ni][mi][3];
;         if (out32) *(float4*)(out32 + (long)m * 1024 + n) = o;
;         else {
;           uint2 ob; ob.x = pack2(o.x, o.y); ob.y = pack2(o.z, o.w);
;           *(uint2*)(xs + (long)m * LDX + n) = ob;
.LBB0_326:
	s_waitcnt vmcnt(0)
	v_pk_add_f32 v[62:63], v[66:67], v[62:63]
	v_pk_add_f32 v[64:65], v[68:69], v[64:65]
	v_cvt_pk_bf16_f32 v66, v62, v63
	v_cvt_pk_bf16_f32 v67, v64, v65
	s_and_b64 vcc, exec, s[40:41]
	v_mov_b32_e32 v200, v66
	v_mov_b32_e32 v201, v67
	s_cbranch_vccnz .LBB0_339
	global_load_dwordx4 v[62:65], v[72:73], off offset:64 nt
	s_cbranch_execnz .LBB0_329

; DEVI float lo2f(unsigned u) { return __uint_as_float(u << 16); }
; DEVI float hi2f(unsigned u) { return __uint_as_float(u & 0xffff0000u); }
; DEVI void phase_resid_gemm(const Params& p, const bfu* A, int lda, int nkt, const bfu* wT, int ldb, const float* resid32,
;                            float* ssq_out, float* out32, char* lds) {
;     ...
;       for (int ni = 0; ni < 4; ++ni) {
;         const int n = n0 + wn * 64 + ni * 16 + fq * 4;
;         float4 r;
;         if (resid32) r = *(const float4*)(resid32 + (long)m * 1024 + n);
;         else { const uint2 u = *(const uint2*)(xs + (long)m * LDX + n); r = make_float4(lo2f(u.x), hi2f(u.x), lo2f(u.y), hi2f(u.y)); }
;         float4 o;
;         o.x = r.x + acc[ni][mi][0]; o.y = r.y + acc[ni][mi][1]; o.z = r.z + acc[ni][mi][2]; o.w = r.w + acc[ni][mi][3];
;         if (out32) *(float4*)(out32 + (long)m * 1024 + n) = o;
;         else {
;           uint2 ob; ob.x = pack2(o.x, o.y); ob.y = pack2(o.z, o.w);
;           *(uint2*)(xs + (long)m * LDX + n) = ob;
.LBB0_329:
	s_waitcnt vmcnt(0)
	v_pk_add_f32 v[58:59], v[58:59], v[62:63]
	v_pk_add_f32 v[60:61], v[60:61], v[64:65]
	v_cvt_pk_bf16_f32 v62, v58, v59
	v_cvt_pk_bf16_f32 v63, v60, v61
	s_and_b64 vcc, exec, s[40:41]
	v_mov_b32_e32 v206, v62
	v_mov_b32_e32 v207, v63
	v_mov_b32_e32 v204, v200
	v_mov_b32_e32 v205, v201
	v_lshl_add_u64 v[212:213], v[70:71], 0, v[254:255]
	s_nop 0
	v_permlane16_swap_b32_e32 v204, v206
	v_permlane16_swap_b32_e32 v205, v207
	s_nop 1
	global_store_dwordx4 v[212:213], v[204:207], off
	s_cbranch_vccnz .LBB0_340
	global_load_dwordx4 v[58:61], v[72:73], off offset:128 nt
	s_cbranch_execnz .LBB0_332

; DEVI float lo2f(unsigned u) { return __uint_as_float(u << 16); }
; DEVI float hi2f(unsigned u) { return __uint_as_float(u & 0xffff0000u); }
; DEVI void phase_resid_gemm(const Params& p, const bfu* A, int lda, int nkt, const bfu* wT, int ldb, const float* resid32,
;                            float* ssq_out, float* out32, char* lds) {
;     ...
;       for (int ni = 0; ni < 4; ++ni) {
;         const int n = n0 + wn * 64 + ni * 16 + fq * 4;
;         float4 r;
;         if (resid32) r = *(const float4*)(resid32 + (long)m * 1024 + n);
;         else { const uint2 u = *(const uint2*)(xs + (long)m * LDX + n); r = make_float4(lo2f(u.x), hi2f(u.x), lo2f(u.y), hi2f(u.y)); }
;         float4 o;
;         o.x = r.x + acc[ni][mi][0]; o.y = r.y + acc[ni][mi][1]; o.z = r.z + acc[ni][mi][2]; o.w = r.w + acc[ni][mi][3];
;         if (out32) *(float4*)(out32 + (long)m * 1024 + n) = o;
;         else {
;           uint2 ob; ob.x = pack2(o.x, o.y); ob.y = pack2(o.z, o.w);
;           *(uint2*)(xs + (long)m * LDX + n) = ob;
.LBB0_332:
	s_waitcnt vmcnt(0)
	v_pk_add_f32 v[54:55], v[54:55], v[58:59]
	v_pk_add_f32 v[56:57], v[56:57], v[60:61]
	v_cvt_pk_bf16_f32 v58, v54, v55
	v_cvt_pk_bf16_f32 v59, v56, v57
	s_and_b64 vcc, exec, s[40:41]
	v_mov_b32_e32 v200, v58
	v_mov_b32_e32 v201, v59
	s_cbranch_vccnz .LBB0_341
	global_load_dwordx4 v[54:57], v[72:73], off offset:192 nt
	s_cbranch_execnz .LBB0_335

; DEVI float lo2f(unsigned u) { return __uint_as_float(u << 16); }
; DEVI float hi2f(unsigned u) { return __uint_as_float(u & 0xffff0000u); }
; DEVI void phase_resid_gemm(const Params& p, const bfu* A, int lda, int nkt, const bfu* wT, int ldb, const float* resid32,
;                            float* ssq_out, float* out32, char* lds) {
;     ...
;     for (int mi = 0; mi < 8; ++mi) {
;       const int m = m0 + wm * 128 + mi * 16 + fr;
;       float ss = 0.f;
; #pragma unroll
;       for (int ni = 0; ni < 4; ++ni) {
;         const int n = n0 + wn * 64 + ni * 16 + fq * 4;
;         float4 r;
;         if (resid32) r = *(const float4*)(resid32 + (long)m * 1024 + n);
;         else { const uint2 u = *(const uint2*)(xs + (long)m * LDX + n); r = make_float4(lo2f(u.x), hi2f(u.x), lo2f(u.y), hi2f(u.y)); }
;         float4 o;
;         o.x = r.x + acc[ni][mi][0]; o.y = r.y + acc[ni][mi][1]; o.z = r.z + acc[ni][mi][2]; o.w = r.w + acc[ni][mi][3];
.LBB0_337:
	s_or_b64 exec, exec, s[36:37]
	v_or_b32_e32 v54, 0x50, v132
	v_ashrrev_i32_e32 v55, 31, v54
	s_waitcnt lgkmcnt(0)
	v_lshlrev_b64 v[46:47], 12, v[54:55]
	v_lshl_add_u64 v[46:47], s[0:1], 0, v[46:47]
	s_and_b64 vcc, exec, s[40:41]
	v_lshl_add_u64 v[56:57], v[130:131], 2, v[46:47]
	s_cbranch_vccnz .LBB0_342
	global_load_dwordx4 v[46:49], v[56:57], off nt
	s_mov_b64 s[36:37], 0
	s_branch .LBB0_343

; DEVI float lo2f(unsigned u) { return __uint_as_float(u << 16); }
; DEVI float hi2f(unsigned u) { return __uint_as_float(u & 0xffff0000u); }
; DEVI void phase_resid_gemm(const Params& p, const bfu* A, int lda, int nkt, const bfu* wT, int ldb, const float* resid32,
;                            float* ssq_out, float* out32, char* lds) {
;     ...
;       for (int ni = 0; ni < 4; ++ni) {
;         const int n = n0 + wn * 64 + ni * 16 + fq * 4;
;         float4 r;
;         if (resid32) r = *(const float4*)(resid32 + (long)m * 1024 + n);
;         else { const uint2 u = *(const uint2*)(xs + (long)m * LDX + n); r = make_float4(lo2f(u.x), hi2f(u.x), lo2f(u.y), hi2f(u.y)); }
;         float4 o;
;         o.x = r.x + acc[ni][mi][0]; o.y = r.y + acc[ni][mi][1]; o.z = r.z + acc[ni][mi][2]; o.w = r.w + acc[ni][mi][3];
;         if (out32) *(float4*)(out32 + (long)m * 1024 + n) = o;
;         else {
;           uint2 ob; ob.x = pack2(o.x, o.y); ob.y = pack2(o.z, o.w);
;           *(uint2*)(xs + (long)m * LDX + n) = ob;
.LBB0_345:
	s_waitcnt vmcnt(0)
	v_pk_add_f32 v[46:47], v[50:51], v[46:47]
	v_pk_add_f32 v[48:49], v[52:53], v[48:49]
	v_cvt_pk_bf16_f32 v50, v46, v47
	v_cvt_pk_bf16_f32 v51, v48, v49
	s_and_b64 vcc, exec, s[40:41]
	v_mov_b32_e32 v200, v50
	v_mov_b32_e32 v201, v51
	s_cbranch_vccnz .LBB0_358
	global_load_dwordx4 v[46:49], v[56:57], off offset:64 nt
	s_cbranch_execnz .LBB0_348

; DEVI float lo2f(unsigned u) { return __uint_as_float(u << 16); }
; DEVI float hi2f(unsigned u) { return __uint_as_float(u & 0xffff0000u); }
; DEVI void phase_resid_gemm(const Params& p, const bfu* A, int lda, int nkt, const bfu* wT, int ldb, const float* resid32,
;                            float* ssq_out, float* out32, char* lds) {
;     ...
;       for (int ni = 0; ni < 4; ++ni) {
;         const int n = n0 + wn * 64 + ni * 16 + fq * 4;
;         float4 r;
;         if (resid32) r = *(const float4*)(resid32 + (long)m * 1024 + n);
;         else { const uint2 u = *(const uint2*)(xs + (long)m * LDX + n); r = make_float4(lo2f(u.x), hi2f(u.x), lo2f(u.y), hi2f(u.y)); }
;         float4 o;
;         o.x = r.x + acc[ni][mi][0]; o.y = r.y + acc[ni][mi][1]; o.z = r.z + acc[ni][mi][2]; o.w = r.w + acc[ni][mi][3];
;         if (out32) *(float4*)(out32 + (long)m * 1024 + n) = o;
;         else {
;           uint2 ob; ob.x = pack2(o.x, o.y); ob.y = pack2(o.z, o.w);
;           *(uint2*)(xs + (long)m * LDX + n) = ob;
.LBB0_348:
	s_waitcnt vmcnt(0)
	v_pk_add_f32 v[42:43], v[42:43], v[46:47]
	v_pk_add_f32 v[44:45], v[44:45], v[48:49]
	v_cvt_pk_bf16_f32 v46, v42, v43
	v_cvt_pk_bf16_f32 v47, v44, v45
	s_and_b64 vcc, exec, s[40:41]
	v_mov_b32_e32 v206, v46
	v_mov_b32_e32 v207, v47
	v_mov_b32_e32 v204, v200
	v_mov_b32_e32 v205, v201
	v_lshl_add_u64 v[212:213], v[54:55], 0, v[254:255]
	s_nop 0
	v_permlane16_swap_b32_e32 v204, v206
	v_permlane16_swap_b32_e32 v205, v207
	s_nop 1
	global_store_dwordx4 v[212:213], v[204:207], off
	s_cbranch_vccnz .LBB0_359
	global_load_dwordx4 v[42:45], v[56:57], off offset:128 nt
	s_cbranch_execnz .LBB0_351

; DEVI float lo2f(unsigned u) { return __uint_as_float(u << 16); }
; DEVI float hi2f(unsigned u) { return __uint_as_float(u & 0xffff0000u); }
; DEVI void phase_resid_gemm(const Params& p, const bfu* A, int lda, int nkt, const bfu* wT, int ldb, const float* resid32,
;                            float* ssq_out, float* out32, char* lds) {
;     ...
;       for (int ni = 0; ni < 4; ++ni) {
;         const int n = n0 + wn * 64 + ni * 16 + fq * 4;
;         float4 r;
;         if (resid32) r = *(const float4*)(resid32 + (long)m * 1024 + n);
;         else { const uint2 u = *(const uint2*)(xs + (long)m * LDX + n); r = make_float4(lo2f(u.x), hi2f(u.x), lo2f(u.y), hi2f(u.y)); }
;         float4 o;
;         o.x = r.x + acc[ni][mi][0]; o.y = r.y + acc[ni][mi][1]; o.z = r.z + acc[ni][mi][2]; o.w = r.w + acc[ni][mi][3];
;         if (out32) *(float4*)(out32 + (long)m * 1024 + n) = o;
;         else {
;           uint2 ob; ob.x = pack2(o.x, o.y); ob.y = pack2(o.z, o.w);
;           *(uint2*)(xs + (long)m * LDX + n) = ob;
.LBB0_351:
	s_waitcnt vmcnt(0)
	v_pk_add_f32 v[38:39], v[38:39], v[42:43]
	v_pk_add_f32 v[40:41], v[40:41], v[44:45]
	v_cvt_pk_bf16_f32 v42, v38, v39
	v_cvt_pk_bf16_f32 v43, v40, v41
	s_and_b64 vcc, exec, s[40:41]
	v_mov_b32_e32 v200, v42
	v_mov_b32_e32 v201, v43
	s_cbranch_vccnz .LBB0_360
	global_load_dwordx4 v[38:41], v[56:57], off offset:192 nt
	s_cbranch_execnz .LBB0_354

; DEVI float lo2f(unsigned u) { return __uint_as_float(u << 16); }
; DEVI float hi2f(unsigned u) { return __uint_as_float(u & 0xffff0000u); }
; DEVI void phase_resid_gemm(const Params& p, const bfu* A, int lda, int nkt, const bfu* wT, int ldb, const float* resid32,
;                            float* ssq_out, float* out32, char* lds) {
;     ...
;     for (int mi = 0; mi < 8; ++mi) {
;       const int m = m0 + wm * 128 + mi * 16 + fr;
;       float ss = 0.f;
; #pragma unroll
;       for (int ni = 0; ni < 4; ++ni) {
;         const int n = n0 + wn * 64 + ni * 16 + fq * 4;
;         float4 r;
;         if (resid32) r = *(const float4*)(resid32 + (long)m * 1024 + n);
;         else { const uint2 u = *(const uint2*)(xs + (long)m * LDX + n); r = make_float4(lo2f(u.x), hi2f(u.x), lo2f(u.y), hi2f(u.y)); }
;         float4 o;
;         o.x = r.x + acc[ni][mi][0]; o.y = r.y + acc[ni][mi][1]; o.z = r.z + acc[ni][mi][2]; o.w = r.w + acc[ni][mi][3];
.LBB0_356:
	s_or_b64 exec, exec, s[36:37]
	v_or_b32_e32 v38, 0x60, v132
	v_ashrrev_i32_e32 v39, 31, v38
	s_waitcnt lgkmcnt(0)
	v_lshlrev_b64 v[30:31], 12, v[38:39]
	v_lshl_add_u64 v[30:31], s[0:1], 0, v[30:31]
	s_and_b64 vcc, exec, s[40:41]
	v_lshl_add_u64 v[40:41], v[130:131], 2, v[30:31]
	s_cbranch_vccnz .LBB0_361
	global_load_dwordx4 v[30:33], v[40:41], off nt
	s_mov_b64 s[36:37], 0
	s_branch .LBB0_362

; DEVI float lo2f(unsigned u) { return __uint_as_float(u << 16); }
; DEVI float hi2f(unsigned u) { return __uint_as_float(u & 0xffff0000u); }
; DEVI void phase_resid_gemm(const Params& p, const bfu* A, int lda, int nkt, const bfu* wT, int ldb, const float* resid32,
;                            float* ssq_out, float* out32, char* lds) {
;     ...
;       for (int ni = 0; ni < 4; ++ni) {
;         const int n = n0 + wn * 64 + ni * 16 + fq * 4;
;         float4 r;
;         if (resid32) r = *(const float4*)(resid32 + (long)m * 1024 + n);
;         else { const uint2 u = *(const uint2*)(xs + (long)m * LDX + n); r = make_float4(lo2f(u.x), hi2f(u.x), lo2f(u.y), hi2f(u.y)); }
;         float4 o;
;         o.x = r.x + acc[ni][mi][0]; o.y = r.y + acc[ni][mi][1]; o.z = r.z + acc[ni][mi][2]; o.w = r.w + acc[ni][mi][3];
;         if (out32) *(float4*)(out32 + (long)m * 1024 + n) = o;
;         else {
;           uint2 ob; ob.x = pack2(o.x, o.y); ob.y = pack2(o.z, o.w);
;           *(uint2*)(xs + (long)m * LDX + n) = ob;
.LBB0_364:
	s_waitcnt vmcnt(0)
	v_pk_add_f32 v[30:31], v[34:35], v[30:31]
	v_pk_add_f32 v[32:33], v[36:37], v[32:33]
	v_cvt_pk_bf16_f32 v34, v30, v31
	v_cvt_pk_bf16_f32 v35, v32, v33
	s_and_b64 vcc, exec, s[40:41]
	v_mov_b32_e32 v200, v34
	v_mov_b32_e32 v201, v35
	s_cbranch_vccnz .LBB0_377
	global_load_dwordx4 v[30:33], v[40:41], off offset:64 nt
	s_cbranch_execnz .LBB0_367

; DEVI float lo2f(unsigned u) { return __uint_as_float(u << 16); }
; DEVI float hi2f(unsigned u) { return __uint_as_float(u & 0xffff0000u); }
; DEVI void phase_resid_gemm(const Params& p, const bfu* A, int lda, int nkt, const bfu* wT, int ldb, const float* resid32,
;                            float* ssq_out, float* out32, char* lds) {
;     ...
;       for (int ni = 0; ni < 4; ++ni) {
;         const int n = n0 + wn * 64 + ni * 16 + fq * 4;
;         float4 r;
;         if (resid32) r = *(const float4*)(resid32 + (long)m * 1024 + n);
;         else { const uint2 u = *(const uint2*)(xs + (long)m * LDX + n); r = make_float4(lo2f(u.x), hi2f(u.x), lo2f(u.y), hi2f(u.y)); }
;         float4 o;
;         o.x = r.x + acc[ni][mi][0]; o.y = r.y + acc[ni][mi][1]; o.z = r.z + acc[ni][mi][2]; o.w = r.w + acc[ni][mi][3];
;         if (out32) *(float4*)(out32 + (long)m * 1024 + n) = o;
;         else {
;           uint2 ob; ob.x = pack2(o.x, o.y); ob.y = pack2(o.z, o.w);
;           *(uint2*)(xs + (long)m * LDX + n) = ob;
.LBB0_367:
	s_waitcnt vmcnt(0)
	v_pk_add_f32 v[26:27], v[26:27], v[30:31]
	v_pk_add_f32 v[28:29], v[28:29], v[32:33]
	v_cvt_pk_bf16_f32 v30, v26, v27
	v_cvt_pk_bf16_f32 v31, v28, v29
	s_and_b64 vcc, exec, s[40:41]
	v_mov_b32_e32 v206, v30
	v_mov_b32_e32 v207, v31
	v_mov_b32_e32 v204, v200
	v_mov_b32_e32 v205, v201
	v_lshl_add_u64 v[212:213], v[38:39], 0, v[254:255]
	s_nop 0
	v_permlane16_swap_b32_e32 v204, v206
	v_permlane16_swap_b32_e32 v205, v207
	s_nop 1
	global_store_dwordx4 v[212:213], v[204:207], off
	s_cbranch_vccnz .LBB0_378
	global_load_dwordx4 v[26:29], v[40:41], off offset:128 nt
	s_cbranch_execnz .LBB0_370

; DEVI float lo2f(unsigned u) { return __uint_as_float(u << 16); }
; DEVI float hi2f(unsigned u) { return __uint_as_float(u & 0xffff0000u); }
; DEVI void phase_resid_gemm(const Params& p, const bfu* A, int lda, int nkt, const bfu* wT, int ldb, const float* resid32,
;                            float* ssq_out, float* out32, char* lds) {
;     ...
;       for (int ni = 0; ni < 4; ++ni) {
;         const int n = n0 + wn * 64 + ni * 16 + fq * 4;
;         float4 r;
;         if (resid32) r = *(const float4*)(resid32 + (long)m * 1024 + n);
;         else { const uint2 u = *(const uint2*)(xs + (long)m * LDX + n); r = make_float4(lo2f(u.x), hi2f(u.x), lo2f(u.y), hi2f(u.y)); }
;         float4 o;
;         o.x = r.x + acc[ni][mi][0]; o.y = r.y + acc[ni][mi][1]; o.z = r.z + acc[ni][mi][2]; o.w = r.w + acc[ni][mi][3];
;         if (out32) *(float4*)(out32 + (long)m * 1024 + n) = o;
;         else {
;           uint2 ob; ob.x = pack2(o.x, o.y); ob.y = pack2(o.z, o.w);
;           *(uint2*)(xs + (long)m * LDX + n) = ob;
.LBB0_370:
	s_waitcnt vmcnt(0)
	v_pk_add_f32 v[22:23], v[22:23], v[26:27]
	v_pk_add_f32 v[24:25], v[24:25], v[28:29]
	v_cvt_pk_bf16_f32 v26, v22, v23
	v_cvt_pk_bf16_f32 v27, v24, v25
	s_and_b64 vcc, exec, s[40:41]
	v_mov_b32_e32 v200, v26
	v_mov_b32_e32 v201, v27
	s_cbranch_vccnz .LBB0_379
	global_load_dwordx4 v[22:25], v[40:41], off offset:192 nt
	s_cbranch_execnz .LBB0_373

; DEVI float lo2f(unsigned u) { return __uint_as_float(u << 16); }
; DEVI float hi2f(unsigned u) { return __uint_as_float(u & 0xffff0000u); }
; DEVI void phase_resid_gemm(const Params& p, const bfu* A, int lda, int nkt, const bfu* wT, int ldb, const float* resid32,
;                            float* ssq_out, float* out32, char* lds) {
;     ...
;     for (int mi = 0; mi < 8; ++mi) {
;       const int m = m0 + wm * 128 + mi * 16 + fr;
;       float ss = 0.f;
; #pragma unroll
;       for (int ni = 0; ni < 4; ++ni) {
;         const int n = n0 + wn * 64 + ni * 16 + fq * 4;
;         float4 r;
;         if (resid32) r = *(const float4*)(resid32 + (long)m * 1024 + n);
;         else { const uint2 u = *(const uint2*)(xs + (long)m * LDX + n); r = make_float4(lo2f(u.x), hi2f(u.x), lo2f(u.y), hi2f(u.y)); }
;         float4 o;
;         o.x = r.x + acc[ni][mi][0]; o.y = r.y + acc[ni][mi][1]; o.z = r.z + acc[ni][mi][2]; o.w = r.w + acc[ni][mi][3];
.LBB0_375:
	s_or_b64 exec, exec, s[36:37]
	v_or_b32_e32 v22, 0x70, v132
	v_ashrrev_i32_e32 v23, 31, v22
	s_waitcnt lgkmcnt(0)
	v_lshlrev_b64 v[14:15], 12, v[22:23]
	v_lshl_add_u64 v[14:15], s[0:1], 0, v[14:15]
	s_and_b64 vcc, exec, s[40:41]
	v_lshl_add_u64 v[24:25], v[130:131], 2, v[14:15]
	s_cbranch_vccnz .LBB0_380
	global_load_dwordx4 v[14:17], v[24:25], off nt
	s_mov_b64 s[36:37], 0
	s_branch .LBB0_381

; DEVI float lo2f(unsigned u) { return __uint_as_float(u << 16); }
; DEVI float hi2f(unsigned u) { return __uint_as_float(u & 0xffff0000u); }
; DEVI void phase_resid_gemm(const Params& p, const bfu* A, int lda, int nkt, const bfu* wT, int ldb, const float* resid32,
;                            float* ssq_out, float* out32, char* lds) {
;     ...
;       for (int ni = 0; ni < 4; ++ni) {
;         const int n = n0 + wn * 64 + ni * 16 + fq * 4;
;         float4 r;
;         if (resid32) r = *(const float4*)(resid32 + (long)m * 1024 + n);
;         else { const uint2 u = *(const uint2*)(xs + (long)m * LDX + n); r = make_float4(lo2f(u.x), hi2f(u.x), lo2f(u.y), hi2f(u.y)); }
;         float4 o;
;         o.x = r.x + acc[ni][mi][0]; o.y = r.y + acc[ni][mi][1]; o.z = r.z + acc[ni][mi][2]; o.w = r.w + acc[ni][mi][3];
;         if (out32) *(float4*)(out32 + (long)m * 1024 + n) = o;
;         else {
;           uint2 ob; ob.x = pack2(o.x, o.y); ob.y = pack2(o.z, o.w);
;           *(uint2*)(xs + (long)m * LDX + n) = ob;
.LBB0_383:
	s_waitcnt vmcnt(0)
	v_pk_add_f32 v[14:15], v[18:19], v[14:15]
	v_pk_add_f32 v[16:17], v[20:21], v[16:17]
	v_cvt_pk_bf16_f32 v18, v14, v15
	v_cvt_pk_bf16_f32 v19, v16, v17
	s_and_b64 vcc, exec, s[40:41]
	v_mov_b32_e32 v200, v18
	v_mov_b32_e32 v201, v19
	s_cbranch_vccnz .LBB0_396
	global_load_dwordx4 v[14:17], v[24:25], off offset:64 nt
	s_cbranch_execnz .LBB0_386

; DEVI float lo2f(unsigned u) { return __uint_as_float(u << 16); }
; DEVI float hi2f(unsigned u) { return __uint_as_float(u & 0xffff0000u); }
; DEVI void phase_resid_gemm(const Params& p, const bfu* A, int lda, int nkt, const bfu* wT, int ldb, const float* resid32,
;                            float* ssq_out, float* out32, char* lds) {
;     ...
;       for (int ni = 0; ni < 4; ++ni) {
;         const int n = n0 + wn * 64 + ni * 16 + fq * 4;
;         float4 r;
;         if (resid32) r = *(const float4*)(resid32 + (long)m * 1024 + n);
;         else { const uint2 u = *(const uint2*)(xs + (long)m * LDX + n); r = make_float4(lo2f(u.x), hi2f(u.x), lo2f(u.y), hi2f(u.y)); }
;         float4 o;
;         o.x = r.x + acc[ni][mi][0]; o.y = r.y + acc[ni][mi][1]; o.z = r.z + acc[ni][mi][2]; o.w = r.w + acc[ni][mi][3];
;         if (out32) *(float4*)(out32 + (long)m * 1024 + n) = o;
;         else {
;           uint2 ob; ob.x = pack2(o.x, o.y); ob.y = pack2(o.z, o.w);
;           *(uint2*)(xs + (long)m * LDX + n) = ob;
.LBB0_386:
	s_waitcnt vmcnt(0)
	v_pk_add_f32 v[10:11], v[10:11], v[14:15]
	v_pk_add_f32 v[12:13], v[12:13], v[16:17]
	v_cvt_pk_bf16_f32 v14, v10, v11
	v_cvt_pk_bf16_f32 v15, v12, v13
	s_and_b64 vcc, exec, s[40:41]
	v_mov_b32_e32 v206, v14
	v_mov_b32_e32 v207, v15
	v_mov_b32_e32 v204, v200
	v_mov_b32_e32 v205, v201
	v_lshl_add_u64 v[212:213], v[22:23], 0, v[254:255]
	s_nop 0
	v_permlane16_swap_b32_e32 v204, v206
	v_permlane16_swap_b32_e32 v205, v207
	s_nop 1
	global_store_dwordx4 v[212:213], v[204:207], off
	s_cbranch_vccnz .LBB0_397
	global_load_dwordx4 v[10:13], v[24:25], off offset:128 nt
	s_cbranch_execnz .LBB0_389

; DEVI float lo2f(unsigned u) { return __uint_as_float(u << 16); }
; DEVI float hi2f(unsigned u) { return __uint_as_float(u & 0xffff0000u); }
; DEVI void phase_resid_gemm(const Params& p, const bfu* A, int lda, int nkt, const bfu* wT, int ldb, const float* resid32,
;                            float* ssq_out, float* out32, char* lds) {
;     ...
;       for (int ni = 0; ni < 4; ++ni) {
;         const int n = n0 + wn * 64 + ni * 16 + fq * 4;
;         float4 r;
;         if (resid32) r = *(const float4*)(resid32 + (long)m * 1024 + n);
;         else { const uint2 u = *(const uint2*)(xs + (long)m * LDX + n); r = make_float4(lo2f(u.x), hi2f(u.x), lo2f(u.y), hi2f(u.y)); }
;         float4 o;
;         o.x = r.x + acc[ni][mi][0]; o.y = r.y + acc[ni][mi][1]; o.z = r.z + acc[ni][mi][2]; o.w = r.w + acc[ni][mi][3];
;         if (out32) *(float4*)(out32 + (long)m * 1024 + n) = o;
;         else {
;           uint2 ob; ob.x = pack2(o.x, o.y); ob.y = pack2(o.z, o.w);
;           *(uint2*)(xs + (long)m * LDX + n) = ob;
.LBB0_389:
	s_waitcnt vmcnt(0)
	v_pk_add_f32 v[6:7], v[6:7], v[10:11]
	v_pk_add_f32 v[8:9], v[8:9], v[12:13]
	v_cvt_pk_bf16_f32 v10, v6, v7
	v_cvt_pk_bf16_f32 v11, v8, v9
	s_and_b64 vcc, exec, s[40:41]
	v_mov_b32_e32 v200, v10
	v_mov_b32_e32 v201, v11
	s_cbranch_vccnz .LBB0_398
	global_load_dwordx4 v[6:9], v[24:25], off offset:192 nt
	s_cbranch_execnz .LBB0_392
